# E9 + in-proj rope epilogue fully pipelined: next 16-row block's rope-table quads prefetched double-buffered before the current block's stores, waits count only the prefetch
# speedup vs baseline: 1.0034x; 1.0034x over previous
;     __device__ __forceinline__ void operator()(const f32x4 (&acc)[2][2][4][2], const Unit& u, int wr, int wc, int fr, int fq) const {
;     ...
;             const bool nrm = (pn < 15) || (wc < 2); const float* nw = (pn < 15) ? qnw : knw; const float sc = (pn < 15) ? C2 : 1.f;
;             f32x4 wv[2][2];
; #pragma unroll
;             for (int bj = 0; bj < 2; ++bj)
; #pragma unroll
;                 for (int n = 0; n < 2; ++n) wv[bj][n] = *(const f32x4*)(nw + 32 * bj + 8 * fq + 4 * n);
; #pragma unroll
;             for (int ai = 0; ai < 2; ++ai)
; #pragma unroll
;                 for (int m = 0; m < 4; ++m) { const int row = row0 + ai * HALF + m * 16; bf16_t* rowp = PROJ + (size_t)row * PP + pn * 256 + 64 * wc + 8 * fq;
;                     f32x4 v[2][2];
; #pragma unroll
;                     for (int bj = 0; bj < 2; ++bj)
; #pragma unroll
;                         for (int n = 0; n < 2; ++n) v[bj][n] = acc[ai][bj][m][n];
;                     if (nrm) {
;                         float ss = 0.f;
; #pragma unroll
;                         for (int bj = 0; bj < 2; ++bj)
; #pragma unroll
;                             for (int n = 0; n < 2; ++n) ss += v[bj][n][0] * v[bj][n][0] + v[bj][n][1] * v[bj][n][1] + v[bj][n][2] * v[bj][n][2] + v[bj][n][3] * v[bj][n][3];
;                         ss += __shfl_xor(ss, 16); ss += __shfl_xor(ss, 32);
;                         const float rinv = __builtin_amdgcn_rsqf(ss * (1.f / 64.f) + EPS);
; #pragma unroll
;                         for (int bj = 0; bj < 2; ++bj)
; #pragma unroll
;                             for (int n = 0; n < 2; ++n) { const f32x4 x = v[bj][n] * wv[bj][n] * rinv; const f32x4 cs = *(const f32x4*)(CS + ((size_t)row * 32 + 16 * bj + 4 * fq + 2 * n) * 2);
;                                 f32x4 o; o[0] = x[0] * cs[0] - x[1] * cs[1]; o[1] = x[0] * cs[1] + x[1] * cs[0]; o[2] = x[2] * cs[2] - x[3] * cs[3]; o[3] = x[2] * cs[3] + x[3] * cs[2]; v[bj][n] = o * sc; }
.LBB0_270:
	s_and_b64 vcc, exec, s[4:5]
	s_cbranch_vccz .LBB0_295
	s_mov_b64 s[98:99], 0x1000
	s_mov_b64 s[100:101], 0x5000
	s_cmp_lt_u32 s16, 15
	v_readlane_b32 s4, v255, 58
	s_cselect_b64 vcc, -1, 0
	v_readlane_b32 s5, v255, 59
	s_or_b64 s[56:57], vcc, s[4:5]
	s_and_b64 s[4:5], vcc, exec
	s_cselect_b32 s4, s12, s14
	s_cselect_b32 s5, s13, s15
	s_add_u32 s4, s4, s38
	v_lshlrev_b32_e32 v178, 3, v173
	s_addc_u32 s5, s5, s39
	v_ashrrev_i32_e32 v179, 31, v178
	v_lshl_add_u64 v[132:133], v[178:179], 2, s[4:5]
	global_load_dwordx4 v[136:139], v[132:133], off offset:16
	global_load_dwordx4 v[140:143], v[132:133], off
	global_load_dwordx4 v[128:131], v[132:133], off offset:144
	s_nop 0
	global_load_dwordx4 v[132:135], v[132:133], off offset:128
	v_cndmask_b32_e64 v144, 0, 1, s[56:57]
	v_cndmask_b32_e32 v176, 1.0, v233, vcc
	v_lshlrev_b32_e32 v182, 2, v173
	v_cmp_ne_u32_e64 s[4:5], 1, v144
	v_mov_b64_e32 v[154:155], v[98:99]
	v_mov_b64_e32 v[158:159], v[122:123]
	v_mov_b64_e32 v[150:151], v[90:91]
	v_mov_b64_e32 v[146:147], v[126:127]
	v_ashrrev_i32_e32 v183, 31, v182
	v_mov_b32_e32 v177, v176
	v_ashrrev_i32_e32 v181, 31, v180
	s_andn2_b64 vcc, exec, s[56:57]
	v_mov_b64_e32 v[152:153], v[96:97]
	v_mov_b64_e32 v[156:157], v[120:121]
	v_mov_b64_e32 v[148:149], v[88:89]
	v_mov_b64_e32 v[144:145], v[124:125]
	s_cbranch_vccnz .LBB0_273
	v_mov_b32_e32 v146, v125
	v_mov_b32_e32 v147, v89
	v_mov_b32_e32 v144, v124
	v_mov_b32_e32 v145, v88
	v_pk_mul_f32 v[146:147], v[146:147], v[146:147]
	v_mov_b32_e32 v148, v121
	v_pk_fma_f32 v[144:145], v[144:145], v[144:145], v[146:147]
	v_mov_b32_e32 v146, v126
	v_mov_b32_e32 v147, v90
	v_pk_fma_f32 v[144:145], v[146:147], v[146:147], v[144:145]
	v_mov_b32_e32 v146, v127
	v_mov_b32_e32 v147, v91
	v_mov_b32_e32 v149, v97
	v_pk_fma_f32 v[144:145], v[146:147], v[146:147], v[144:145]
	v_mov_b32_e32 v146, v120
	v_mov_b32_e32 v147, v96
	v_pk_mul_f32 v[148:149], v[148:149], v[148:149]
	v_add_f32_e32 v144, v144, v145
	v_pk_fma_f32 v[146:147], v[146:147], v[146:147], v[148:149]
	v_mov_b32_e32 v148, v122
	v_mov_b32_e32 v149, v98
	v_pk_fma_f32 v[146:147], v[148:149], v[148:149], v[146:147]
	v_mov_b32_e32 v148, v123
	v_mov_b32_e32 v149, v99
	v_pk_fma_f32 v[146:147], v[148:149], v[148:149], v[146:147]
	v_mov_b32_e32 v186, v176
	v_add_f32_e32 v144, v144, v146
	v_add_f32_e32 v144, v144, v147
	ds_bpermute_b32 v145, v196, v144
	s_waitcnt vmcnt(0)
	v_pk_mul_f32 v[146:147], v[124:125], v[140:141]
	v_mov_b32_e32 v187, v176
	s_waitcnt lgkmcnt(0)
	v_add_f32_e32 v144, v144, v145
	ds_bpermute_b32 v145, v197, v144
	s_waitcnt lgkmcnt(0)
	v_add_f32_e32 v144, v144, v145
	v_fmamk_f32 v144, v144, 0x3c800000, v253
	v_rsq_f32_e32 v184, v144
	v_pk_mul_f32 v[144:145], v[126:127], v[142:143]
	v_pk_mul_f32 v[154:155], v[146:147], v[184:185] op_sel_hi:[1,0]
	v_pk_mul_f32 v[152:153], v[144:145], v[184:185] op_sel_hi:[1,0]
	v_lshlrev_b64 v[144:145], 8, v[180:181]
	v_lshl_add_u64 v[144:145], s[22:23], 0, v[144:145]
	v_lshl_add_u64 v[156:157], v[182:183], 3, v[144:145]
	global_load_dwordx4 v[148:151], v[156:157], off offset:16
	global_load_dwordx4 v[144:147], v[156:157], off
	global_load_dwordx4 v[240:243], v[156:157], off offset:144
	global_load_dwordx4 v[244:247], v[156:157], off offset:128
	v_lshl_add_u64 v[248:249], v[156:157], 0, s[98:99]
	global_load_dwordx4 v[208:211], v[248:249], off offset:16
	global_load_dwordx4 v[212:215], v[248:249], off
	global_load_dwordx4 v[216:219], v[248:249], off offset:144
	global_load_dwordx4 v[220:223], v[248:249], off offset:128
	s_waitcnt vmcnt(4)
	v_pk_mul_f32 v[158:159], v[144:145], v[154:155] op_sel:[1,1] op_sel_hi:[0,1]
	v_pk_fma_f32 v[190:191], v[144:145], v[154:155], v[158:159] op_sel_hi:[1,0,1] neg_lo:[0,0,1] neg_hi:[0,0,1]
	v_pk_fma_f32 v[144:145], v[144:145], v[154:155], v[158:159] op_sel_hi:[1,0,1]
	v_pk_mul_f32 v[154:155], v[146:147], v[152:153] op_sel:[1,1] op_sel_hi:[0,1]
	v_pk_fma_f32 v[158:159], v[146:147], v[152:153], v[154:155] op_sel_hi:[1,0,1] neg_lo:[0,0,1] neg_hi:[0,0,1]
	v_pk_fma_f32 v[146:147], v[146:147], v[152:153], v[154:155] op_sel_hi:[1,0,1]
	v_pk_mul_f32 v[154:155], v[88:89], v[136:137]
	v_mov_b32_e32 v159, v147
	v_pk_mul_f32 v[152:153], v[90:91], v[138:139]
	v_pk_mul_f32 v[154:155], v[154:155], v[184:185] op_sel_hi:[1,0]
	v_pk_mul_f32 v[146:147], v[186:187], v[158:159]
	v_mov_b32_e32 v191, v145
	v_pk_mul_f32 v[152:153], v[152:153], v[184:185] op_sel_hi:[1,0]
	v_pk_mul_f32 v[158:159], v[148:149], v[154:155] op_sel:[1,1] op_sel_hi:[0,1]
	v_pk_mul_f32 v[144:145], v[176:177], v[190:191]
	v_pk_fma_f32 v[190:191], v[148:149], v[154:155], v[158:159] op_sel_hi:[1,0,1] neg_lo:[0,0,1] neg_hi:[0,0,1]
	v_pk_fma_f32 v[148:149], v[148:149], v[154:155], v[158:159] op_sel_hi:[1,0,1]
	v_pk_mul_f32 v[154:155], v[150:151], v[152:153] op_sel:[1,1] op_sel_hi:[0,1]
	v_pk_fma_f32 v[158:159], v[150:151], v[152:153], v[154:155] op_sel_hi:[1,0,1] neg_lo:[0,0,1] neg_hi:[0,0,1]
	v_pk_fma_f32 v[150:151], v[150:151], v[152:153], v[154:155] op_sel_hi:[1,0,1]
	v_mov_b32_e32 v191, v149
	v_mov_b32_e32 v159, v151
	v_pk_mul_f32 v[152:153], v[122:123], v[134:135]
	v_pk_mul_f32 v[154:155], v[120:121], v[132:133]
	v_pk_mul_f32 v[150:151], v[186:187], v[158:159]
	v_pk_mul_f32 v[148:149], v[176:177], v[190:191]
	v_pk_mul_f32 v[190:191], v[152:153], v[184:185] op_sel_hi:[1,0]
	v_pk_mul_f32 v[200:201], v[154:155], v[184:185] op_sel_hi:[1,0]
	v_mov_b64_e32 v[152:153], v[240:241]
	v_mov_b64_e32 v[154:155], v[242:243]
	v_mov_b64_e32 v[156:157], v[244:245]
	v_mov_b64_e32 v[158:159], v[246:247]
	v_pk_mul_f32 v[202:203], v[156:157], v[200:201] op_sel:[1,1] op_sel_hi:[0,1]
	v_pk_fma_f32 v[204:205], v[156:157], v[200:201], v[202:203] op_sel_hi:[1,0,1] neg_lo:[0,0,1] neg_hi:[0,0,1]
; __device__ __forceinline__ unsigned cvt_pk_bf16(float lo, float hi) { f32x2_c v = {lo, hi}; bf16x2_c b = __builtin_convertvector(v, bf16x2_c); return __builtin_bit_cast(unsigned, b); }
;     __device__ __forceinline__ void operator()(const f32x4 (&acc)[2][2][4][2], const Unit& u, int wr, int wc, int fr, int fq) const {
;     ...
;                 for (int m = 0; m < 4; ++m) { const int row = row0 + ai * HALF + m * 16; bf16_t* rowp = PROJ + (size_t)row * PP + pn * 256 + 64 * wc + 8 * fq;
;                     f32x4 v[2][2];
; #pragma unroll
;                     for (int bj = 0; bj < 2; ++bj)
; #pragma unroll
;                         for (int n = 0; n < 2; ++n) v[bj][n] = acc[ai][bj][m][n];
;                     if (nrm) {
;                         float ss = 0.f;
; #pragma unroll
;                         for (int bj = 0; bj < 2; ++bj)
; #pragma unroll
;                             for (int n = 0; n < 2; ++n) ss += v[bj][n][0] * v[bj][n][0] + v[bj][n][1] * v[bj][n][1] + v[bj][n][2] * v[bj][n][2] + v[bj][n][3] * v[bj][n][3];
;                         ss += __shfl_xor(ss, 16); ss += __shfl_xor(ss, 32);
;                         const float rinv = __builtin_amdgcn_rsqf(ss * (1.f / 64.f) + EPS);
; #pragma unroll
;                         for (int bj = 0; bj < 2; ++bj)
; #pragma unroll
;                             for (int n = 0; n < 2; ++n) { const f32x4 x = v[bj][n] * wv[bj][n] * rinv; const f32x4 cs = *(const f32x4*)(CS + ((size_t)row * 32 + 16 * bj + 4 * fq + 2 * n) * 2);
;                                 f32x4 o; o[0] = x[0] * cs[0] - x[1] * cs[1]; o[1] = x[0] * cs[1] + x[1] * cs[0]; o[2] = x[2] * cs[2] - x[3] * cs[3]; o[3] = x[2] * cs[3] + x[3] * cs[2]; v[bj][n] = o * sc; }
;                     }
; #pragma unroll
;                     for (int bj = 0; bj < 2; ++bj) { u32x4 w; w.x = cvt_pk_bf16(v[bj][0][0], v[bj][0][1]); w.y = cvt_pk_bf16(v[bj][0][2], v[bj][0][3]); w.z = cvt_pk_bf16(v[bj][1][0], v[bj][1][1]); w.w = cvt_pk_bf16(v[bj][1][2], v[bj][1][3]);
;                         *(u32x4*)(rowp + 32 * bj) = w; } }
	v_pk_fma_f32 v[156:157], v[156:157], v[200:201], v[202:203] op_sel_hi:[1,0,1]
	v_pk_mul_f32 v[200:201], v[158:159], v[190:191] op_sel:[1,1] op_sel_hi:[0,1]
	v_pk_fma_f32 v[202:203], v[158:159], v[190:191], v[200:201] op_sel_hi:[1,0,1] neg_lo:[0,0,1] neg_hi:[0,0,1]
	v_pk_fma_f32 v[158:159], v[158:159], v[190:191], v[200:201] op_sel_hi:[1,0,1]
	v_pk_mul_f32 v[190:191], v[98:99], v[130:131]
	v_pk_mul_f32 v[200:201], v[96:97], v[128:129]
	v_pk_mul_f32 v[190:191], v[190:191], v[184:185] op_sel_hi:[1,0]
	v_pk_mul_f32 v[184:185], v[200:201], v[184:185] op_sel_hi:[1,0]
	v_mov_b32_e32 v203, v159
	v_pk_mul_f32 v[200:201], v[152:153], v[184:185] op_sel:[1,1] op_sel_hi:[0,1]
	v_pk_mul_f32 v[158:159], v[186:187], v[202:203]
	v_pk_fma_f32 v[202:203], v[152:153], v[184:185], v[200:201] op_sel_hi:[1,0,1] neg_lo:[0,0,1] neg_hi:[0,0,1]
	v_pk_fma_f32 v[152:153], v[152:153], v[184:185], v[200:201] op_sel_hi:[1,0,1]
	v_pk_mul_f32 v[184:185], v[154:155], v[190:191] op_sel:[1,1] op_sel_hi:[0,1]
	v_pk_fma_f32 v[200:201], v[154:155], v[190:191], v[184:185] op_sel_hi:[1,0,1] neg_lo:[0,0,1] neg_hi:[0,0,1]
	v_pk_fma_f32 v[154:155], v[154:155], v[190:191], v[184:185] op_sel_hi:[1,0,1]
	v_mov_b32_e32 v205, v157
	v_mov_b32_e32 v201, v155
	v_mov_b32_e32 v203, v153
	v_pk_mul_f32 v[156:157], v[176:177], v[204:205]
	v_pk_mul_f32 v[154:155], v[186:187], v[200:201]
	v_pk_mul_f32 v[152:153], v[176:177], v[202:203]
.LBB0_273:
	v_mov_b64_e32 v[184:185], s[24:25]
	v_mad_i64_i32 v[184:185], s[56:57], v180, s64, v[184:185]
	s_lshl_b32 s78, s16, 9
	v_lshl_add_u64 v[184:185], v[184:185], 0, s[78:79]
	s_lshl_b32 s78, s81, 1
	v_lshl_add_u64 v[184:185], v[184:185], 0, s[78:79]
	v_lshl_add_u64 v[184:185], v[178:179], 1, v[184:185]
	v_cvt_pk_bf16_f32 v144, v144, v145
	v_cvt_pk_bf16_f32 v145, v146, v147
	v_cvt_pk_bf16_f32 v146, v148, v149
	v_cvt_pk_bf16_f32 v147, v150, v151
	global_store_dwordx4 v[184:185], v[144:147], off
	v_mov_b64_e32 v[150:151], v[82:83]
	s_and_b64 vcc, exec, s[4:5]
	v_cvt_pk_bf16_f32 v144, v156, v157
	v_cvt_pk_bf16_f32 v145, v158, v159
	v_cvt_pk_bf16_f32 v146, v152, v153
	v_cvt_pk_bf16_f32 v147, v154, v155
	global_store_dwordx4 v[184:185], v[144:147], off offset:64
	v_add_u32_e32 v184, 16, v180
	v_mov_b64_e32 v[154:155], v[86:87]
	v_mov_b64_e32 v[158:159], v[114:115]
	v_mov_b64_e32 v[146:147], v[118:119]
	v_ashrrev_i32_e32 v185, 31, v184
	v_mov_b64_e32 v[152:153], v[84:85]
	v_mov_b64_e32 v[156:157], v[112:113]
	v_mov_b64_e32 v[148:149], v[80:81]
	v_mov_b64_e32 v[144:145], v[116:117]
	s_cbranch_vccnz .LBB0_275
	v_mov_b32_e32 v146, v117
	v_mov_b32_e32 v147, v81
	v_mov_b32_e32 v144, v116
	v_mov_b32_e32 v145, v80
	v_pk_mul_f32 v[146:147], v[146:147], v[146:147]
	v_mov_b32_e32 v148, v113
	v_pk_fma_f32 v[144:145], v[144:145], v[144:145], v[146:147]
	v_mov_b32_e32 v146, v118
	v_mov_b32_e32 v147, v82
	v_pk_fma_f32 v[144:145], v[146:147], v[146:147], v[144:145]
	v_mov_b32_e32 v146, v119
	v_mov_b32_e32 v147, v83
	v_mov_b32_e32 v149, v85
	v_pk_fma_f32 v[144:145], v[146:147], v[146:147], v[144:145]
	v_mov_b32_e32 v146, v112
	v_mov_b32_e32 v147, v84
	v_pk_mul_f32 v[148:149], v[148:149], v[148:149]
	v_add_f32_e32 v144, v144, v145
	v_pk_fma_f32 v[146:147], v[146:147], v[146:147], v[148:149]
	v_mov_b32_e32 v148, v114
	v_mov_b32_e32 v149, v86
	v_pk_fma_f32 v[146:147], v[148:149], v[148:149], v[146:147]
	v_mov_b32_e32 v148, v115
	v_mov_b32_e32 v149, v87
	v_pk_fma_f32 v[146:147], v[148:149], v[148:149], v[146:147]
	v_mov_b32_e32 v190, v176
	v_add_f32_e32 v144, v144, v146
	v_add_f32_e32 v144, v144, v147
	ds_bpermute_b32 v145, v196, v144
	v_pk_mul_f32 v[146:147], v[116:117], v[140:141]
	v_mov_b32_e32 v191, v176
	s_waitcnt lgkmcnt(0)
	v_add_f32_e32 v144, v144, v145
	ds_bpermute_b32 v145, v197, v144
	s_waitcnt lgkmcnt(0)
	v_add_f32_e32 v144, v144, v145
	v_fmamk_f32 v144, v144, 0x3c800000, v253
	v_rsq_f32_e32 v186, v144
	v_pk_mul_f32 v[144:145], v[118:119], v[142:143]
	v_pk_mul_f32 v[154:155], v[146:147], v[186:187] op_sel_hi:[1,0]
	v_pk_mul_f32 v[152:153], v[144:145], v[186:187] op_sel_hi:[1,0]
	v_lshlrev_b64 v[144:145], 8, v[184:185]
	v_lshl_add_u64 v[144:145], s[22:23], 0, v[144:145]
	v_lshl_add_u64 v[156:157], v[182:183], 3, v[144:145]
	s_waitcnt vmcnt(2)
	v_mov_b64_e32 v[148:149], v[208:209]
	v_mov_b64_e32 v[150:151], v[210:211]
	v_mov_b64_e32 v[144:145], v[212:213]
	v_mov_b64_e32 v[146:147], v[214:215]
	v_lshl_add_u64 v[248:249], v[156:157], 0, s[98:99]
	global_load_dwordx4 v[224:227], v[248:249], off offset:16
	global_load_dwordx4 v[228:231], v[248:249], off
	global_load_dwordx4 v[234:237], v[248:249], off offset:144
	global_load_dwordx4 v[238:241], v[248:249], off offset:128
	v_pk_mul_f32 v[158:159], v[144:145], v[154:155] op_sel:[1,1] op_sel_hi:[0,1]
	v_pk_fma_f32 v[200:201], v[144:145], v[154:155], v[158:159] op_sel_hi:[1,0,1] neg_lo:[0,0,1] neg_hi:[0,0,1]
	v_pk_fma_f32 v[144:145], v[144:145], v[154:155], v[158:159] op_sel_hi:[1,0,1]
	v_pk_mul_f32 v[154:155], v[146:147], v[152:153] op_sel:[1,1] op_sel_hi:[0,1]
	v_pk_fma_f32 v[158:159], v[146:147], v[152:153], v[154:155] op_sel_hi:[1,0,1] neg_lo:[0,0,1] neg_hi:[0,0,1]
	v_pk_fma_f32 v[146:147], v[146:147], v[152:153], v[154:155] op_sel_hi:[1,0,1]
	v_pk_mul_f32 v[154:155], v[80:81], v[136:137]
	v_mov_b32_e32 v159, v147
	v_pk_mul_f32 v[152:153], v[82:83], v[138:139]
	v_pk_mul_f32 v[154:155], v[154:155], v[186:187] op_sel_hi:[1,0]
	v_pk_mul_f32 v[146:147], v[190:191], v[158:159]
	v_mov_b32_e32 v201, v145
	v_pk_mul_f32 v[152:153], v[152:153], v[186:187] op_sel_hi:[1,0]
	v_pk_mul_f32 v[158:159], v[148:149], v[154:155] op_sel:[1,1] op_sel_hi:[0,1]
	v_pk_mul_f32 v[144:145], v[176:177], v[200:201]
; __device__ __forceinline__ unsigned cvt_pk_bf16(float lo, float hi) { f32x2_c v = {lo, hi}; bf16x2_c b = __builtin_convertvector(v, bf16x2_c); return __builtin_bit_cast(unsigned, b); }
;     __device__ __forceinline__ void operator()(const f32x4 (&acc)[2][2][4][2], const Unit& u, int wr, int wc, int fr, int fq) const {
;     ...
;                 for (int m = 0; m < 4; ++m) { const int row = row0 + ai * HALF + m * 16; bf16_t* rowp = PROJ + (size_t)row * PP + pn * 256 + 64 * wc + 8 * fq;
;                     f32x4 v[2][2];
; #pragma unroll
;                     for (int bj = 0; bj < 2; ++bj)
; #pragma unroll
;                         for (int n = 0; n < 2; ++n) v[bj][n] = acc[ai][bj][m][n];
;                     if (nrm) {
;                         float ss = 0.f;
; #pragma unroll
;                         for (int bj = 0; bj < 2; ++bj)
; #pragma unroll
;                             for (int n = 0; n < 2; ++n) ss += v[bj][n][0] * v[bj][n][0] + v[bj][n][1] * v[bj][n][1] + v[bj][n][2] * v[bj][n][2] + v[bj][n][3] * v[bj][n][3];
;                         ss += __shfl_xor(ss, 16); ss += __shfl_xor(ss, 32);
;                         const float rinv = __builtin_amdgcn_rsqf(ss * (1.f / 64.f) + EPS);
; #pragma unroll
;                         for (int bj = 0; bj < 2; ++bj)
; #pragma unroll
;                             for (int n = 0; n < 2; ++n) { const f32x4 x = v[bj][n] * wv[bj][n] * rinv; const f32x4 cs = *(const f32x4*)(CS + ((size_t)row * 32 + 16 * bj + 4 * fq + 2 * n) * 2);
;                                 f32x4 o; o[0] = x[0] * cs[0] - x[1] * cs[1]; o[1] = x[0] * cs[1] + x[1] * cs[0]; o[2] = x[2] * cs[2] - x[3] * cs[3]; o[3] = x[2] * cs[3] + x[3] * cs[2]; v[bj][n] = o * sc; }
;                     }
; #pragma unroll
;                     for (int bj = 0; bj < 2; ++bj) { u32x4 w; w.x = cvt_pk_bf16(v[bj][0][0], v[bj][0][1]); w.y = cvt_pk_bf16(v[bj][0][2], v[bj][0][3]); w.z = cvt_pk_bf16(v[bj][1][0], v[bj][1][1]); w.w = cvt_pk_bf16(v[bj][1][2], v[bj][1][3]);
;                         *(u32x4*)(rowp + 32 * bj) = w; } }
	v_pk_fma_f32 v[200:201], v[148:149], v[154:155], v[158:159] op_sel_hi:[1,0,1] neg_lo:[0,0,1] neg_hi:[0,0,1]
	v_pk_fma_f32 v[148:149], v[148:149], v[154:155], v[158:159] op_sel_hi:[1,0,1]
	v_pk_mul_f32 v[154:155], v[150:151], v[152:153] op_sel:[1,1] op_sel_hi:[0,1]
	v_pk_fma_f32 v[158:159], v[150:151], v[152:153], v[154:155] op_sel_hi:[1,0,1] neg_lo:[0,0,1] neg_hi:[0,0,1]
	v_pk_fma_f32 v[150:151], v[150:151], v[152:153], v[154:155] op_sel_hi:[1,0,1]
	v_mov_b32_e32 v201, v149
	v_mov_b32_e32 v159, v151
	v_pk_mul_f32 v[152:153], v[114:115], v[134:135]
	v_pk_mul_f32 v[154:155], v[112:113], v[132:133]
	v_pk_mul_f32 v[150:151], v[190:191], v[158:159]
	v_pk_mul_f32 v[148:149], v[176:177], v[200:201]
	v_pk_mul_f32 v[200:201], v[152:153], v[186:187] op_sel_hi:[1,0]
	v_pk_mul_f32 v[202:203], v[154:155], v[186:187] op_sel_hi:[1,0]
	v_mov_b64_e32 v[152:153], v[216:217]
	v_mov_b64_e32 v[154:155], v[218:219]
	v_mov_b64_e32 v[156:157], v[220:221]
	v_mov_b64_e32 v[158:159], v[222:223]
	v_pk_mul_f32 v[204:205], v[156:157], v[202:203] op_sel:[1,1] op_sel_hi:[0,1]
	v_pk_fma_f32 v[206:207], v[156:157], v[202:203], v[204:205] op_sel_hi:[1,0,1] neg_lo:[0,0,1] neg_hi:[0,0,1]
	v_pk_fma_f32 v[156:157], v[156:157], v[202:203], v[204:205] op_sel_hi:[1,0,1]
	v_pk_mul_f32 v[202:203], v[158:159], v[200:201] op_sel:[1,1] op_sel_hi:[0,1]
	v_pk_fma_f32 v[204:205], v[158:159], v[200:201], v[202:203] op_sel_hi:[1,0,1] neg_lo:[0,0,1] neg_hi:[0,0,1]
	v_pk_fma_f32 v[158:159], v[158:159], v[200:201], v[202:203] op_sel_hi:[1,0,1]
	v_pk_mul_f32 v[200:201], v[86:87], v[130:131]
	v_pk_mul_f32 v[202:203], v[84:85], v[128:129]
	v_pk_mul_f32 v[200:201], v[200:201], v[186:187] op_sel_hi:[1,0]
	v_pk_mul_f32 v[186:187], v[202:203], v[186:187] op_sel_hi:[1,0]
	v_mov_b32_e32 v205, v159
	v_pk_mul_f32 v[202:203], v[152:153], v[186:187] op_sel:[1,1] op_sel_hi:[0,1]
	v_pk_mul_f32 v[158:159], v[190:191], v[204:205]
	v_pk_fma_f32 v[204:205], v[152:153], v[186:187], v[202:203] op_sel_hi:[1,0,1] neg_lo:[0,0,1] neg_hi:[0,0,1]
	v_pk_fma_f32 v[152:153], v[152:153], v[186:187], v[202:203] op_sel_hi:[1,0,1]
	v_pk_mul_f32 v[186:187], v[154:155], v[200:201] op_sel:[1,1] op_sel_hi:[0,1]
	v_pk_fma_f32 v[202:203], v[154:155], v[200:201], v[186:187] op_sel_hi:[1,0,1] neg_lo:[0,0,1] neg_hi:[0,0,1]
	v_pk_fma_f32 v[154:155], v[154:155], v[200:201], v[186:187] op_sel_hi:[1,0,1]
	v_mov_b32_e32 v207, v157
	v_mov_b32_e32 v203, v155
	v_mov_b32_e32 v205, v153
	v_pk_mul_f32 v[156:157], v[176:177], v[206:207]
	v_pk_mul_f32 v[154:155], v[190:191], v[202:203]
	v_pk_mul_f32 v[152:153], v[176:177], v[204:205]
.LBB0_275:
	v_mov_b64_e32 v[186:187], s[24:25]
	s_lshl_b32 s7, s16, 8
	v_mad_i64_i32 v[184:185], s[56:57], v184, s64, v[186:187]
	s_lshl_b32 s56, s7, 1
	s_mov_b32 s57, s79
	v_lshl_add_u64 v[184:185], v[184:185], 0, s[56:57]
	v_lshl_add_u64 v[184:185], v[184:185], 0, s[78:79]
	v_lshl_add_u64 v[184:185], v[178:179], 1, v[184:185]
	v_cvt_pk_bf16_f32 v144, v144, v145
	v_cvt_pk_bf16_f32 v145, v146, v147
	v_cvt_pk_bf16_f32 v146, v148, v149
	v_cvt_pk_bf16_f32 v147, v150, v151
	global_store_dwordx4 v[184:185], v[144:147], off
	v_mov_b64_e32 v[150:151], v[74:75]
	s_and_b64 vcc, exec, s[4:5]
	v_cvt_pk_bf16_f32 v144, v156, v157
	v_cvt_pk_bf16_f32 v145, v158, v159
	v_cvt_pk_bf16_f32 v146, v152, v153
	v_cvt_pk_bf16_f32 v147, v154, v155
	global_store_dwordx4 v[184:185], v[144:147], off offset:64
	v_add_u32_e32 v184, 32, v180
	v_mov_b64_e32 v[154:155], v[78:79]
	v_mov_b64_e32 v[158:159], v[106:107]
	v_mov_b64_e32 v[146:147], v[110:111]
	v_ashrrev_i32_e32 v185, 31, v184
	v_mov_b64_e32 v[152:153], v[76:77]
	v_mov_b64_e32 v[156:157], v[104:105]
	v_mov_b64_e32 v[148:149], v[72:73]
	v_mov_b64_e32 v[144:145], v[108:109]
	s_cbranch_vccnz .LBB0_277
	v_mov_b32_e32 v146, v109
	v_mov_b32_e32 v147, v73
	v_mov_b32_e32 v144, v108
	v_mov_b32_e32 v145, v72
	v_pk_mul_f32 v[146:147], v[146:147], v[146:147]
	v_mov_b32_e32 v148, v105
	v_pk_fma_f32 v[144:145], v[144:145], v[144:145], v[146:147]
	v_mov_b32_e32 v146, v110
	v_mov_b32_e32 v147, v74
	v_pk_fma_f32 v[144:145], v[146:147], v[146:147], v[144:145]
	v_mov_b32_e32 v146, v111
	v_mov_b32_e32 v147, v75
	v_mov_b32_e32 v149, v77
	v_pk_fma_f32 v[144:145], v[146:147], v[146:147], v[144:145]
	v_mov_b32_e32 v146, v104
	v_mov_b32_e32 v147, v76
	v_pk_mul_f32 v[148:149], v[148:149], v[148:149]
	v_add_f32_e32 v144, v144, v145
	v_pk_fma_f32 v[146:147], v[146:147], v[146:147], v[148:149]
	v_mov_b32_e32 v148, v106
	v_mov_b32_e32 v149, v78
	v_pk_fma_f32 v[146:147], v[148:149], v[148:149], v[146:147]
	v_mov_b32_e32 v148, v107
	v_mov_b32_e32 v149, v79
	v_pk_fma_f32 v[146:147], v[148:149], v[148:149], v[146:147]
	v_mov_b32_e32 v190, v176
	v_add_f32_e32 v144, v144, v146
	v_add_f32_e32 v144, v144, v147
	ds_bpermute_b32 v145, v196, v144
	v_pk_mul_f32 v[146:147], v[108:109], v[140:141]
	v_mov_b32_e32 v191, v176
	s_waitcnt lgkmcnt(0)
	v_add_f32_e32 v144, v144, v145
	ds_bpermute_b32 v145, v197, v144
	s_waitcnt lgkmcnt(0)
	v_add_f32_e32 v144, v144, v145
	v_fmamk_f32 v144, v144, 0x3c800000, v253
	v_rsq_f32_e32 v186, v144
	v_pk_mul_f32 v[144:145], v[110:111], v[142:143]
	v_pk_mul_f32 v[154:155], v[146:147], v[186:187] op_sel_hi:[1,0]
	v_pk_mul_f32 v[152:153], v[144:145], v[186:187] op_sel_hi:[1,0]
	v_lshlrev_b64 v[144:145], 8, v[184:185]
	v_lshl_add_u64 v[144:145], s[22:23], 0, v[144:145]
	v_lshl_add_u64 v[156:157], v[182:183], 3, v[144:145]
	s_waitcnt vmcnt(2)
; __device__ __forceinline__ unsigned cvt_pk_bf16(float lo, float hi) { f32x2_c v = {lo, hi}; bf16x2_c b = __builtin_convertvector(v, bf16x2_c); return __builtin_bit_cast(unsigned, b); }
;     __device__ __forceinline__ void operator()(const f32x4 (&acc)[2][2][4][2], const Unit& u, int wr, int wc, int fr, int fq) const {
;     ...
;                 for (int m = 0; m < 4; ++m) { const int row = row0 + ai * HALF + m * 16; bf16_t* rowp = PROJ + (size_t)row * PP + pn * 256 + 64 * wc + 8 * fq;
;                     f32x4 v[2][2];
; #pragma unroll
;                     for (int bj = 0; bj < 2; ++bj)
; #pragma unroll
;                         for (int n = 0; n < 2; ++n) v[bj][n] = acc[ai][bj][m][n];
;                     if (nrm) {
;                         float ss = 0.f;
; #pragma unroll
;                         for (int bj = 0; bj < 2; ++bj)
; #pragma unroll
;                             for (int n = 0; n < 2; ++n) ss += v[bj][n][0] * v[bj][n][0] + v[bj][n][1] * v[bj][n][1] + v[bj][n][2] * v[bj][n][2] + v[bj][n][3] * v[bj][n][3];
;                         ss += __shfl_xor(ss, 16); ss += __shfl_xor(ss, 32);
;                         const float rinv = __builtin_amdgcn_rsqf(ss * (1.f / 64.f) + EPS);
; #pragma unroll
;                         for (int bj = 0; bj < 2; ++bj)
; #pragma unroll
;                             for (int n = 0; n < 2; ++n) { const f32x4 x = v[bj][n] * wv[bj][n] * rinv; const f32x4 cs = *(const f32x4*)(CS + ((size_t)row * 32 + 16 * bj + 4 * fq + 2 * n) * 2);
;                                 f32x4 o; o[0] = x[0] * cs[0] - x[1] * cs[1]; o[1] = x[0] * cs[1] + x[1] * cs[0]; o[2] = x[2] * cs[2] - x[3] * cs[3]; o[3] = x[2] * cs[3] + x[3] * cs[2]; v[bj][n] = o * sc; }
;                     }
; #pragma unroll
;                     for (int bj = 0; bj < 2; ++bj) { u32x4 w; w.x = cvt_pk_bf16(v[bj][0][0], v[bj][0][1]); w.y = cvt_pk_bf16(v[bj][0][2], v[bj][0][3]); w.z = cvt_pk_bf16(v[bj][1][0], v[bj][1][1]); w.w = cvt_pk_bf16(v[bj][1][2], v[bj][1][3]);
;                         *(u32x4*)(rowp + 32 * bj) = w; } }
	v_mov_b64_e32 v[148:149], v[224:225]
	v_mov_b64_e32 v[150:151], v[226:227]
	v_mov_b64_e32 v[144:145], v[228:229]
	v_mov_b64_e32 v[146:147], v[230:231]
	v_lshl_add_u64 v[248:249], v[156:157], 0, s[98:99]
	global_load_dwordx4 v[208:211], v[248:249], off offset:16
	global_load_dwordx4 v[212:215], v[248:249], off
	global_load_dwordx4 v[216:219], v[248:249], off offset:144
	global_load_dwordx4 v[220:223], v[248:249], off offset:128
	v_pk_mul_f32 v[158:159], v[144:145], v[154:155] op_sel:[1,1] op_sel_hi:[0,1]
	v_pk_fma_f32 v[200:201], v[144:145], v[154:155], v[158:159] op_sel_hi:[1,0,1] neg_lo:[0,0,1] neg_hi:[0,0,1]
	v_pk_fma_f32 v[144:145], v[144:145], v[154:155], v[158:159] op_sel_hi:[1,0,1]
	v_pk_mul_f32 v[154:155], v[146:147], v[152:153] op_sel:[1,1] op_sel_hi:[0,1]
	v_pk_fma_f32 v[158:159], v[146:147], v[152:153], v[154:155] op_sel_hi:[1,0,1] neg_lo:[0,0,1] neg_hi:[0,0,1]
	v_pk_fma_f32 v[146:147], v[146:147], v[152:153], v[154:155] op_sel_hi:[1,0,1]
	v_pk_mul_f32 v[154:155], v[72:73], v[136:137]
	v_mov_b32_e32 v159, v147
	v_pk_mul_f32 v[152:153], v[74:75], v[138:139]
	v_pk_mul_f32 v[154:155], v[154:155], v[186:187] op_sel_hi:[1,0]
	v_pk_mul_f32 v[146:147], v[190:191], v[158:159]
	v_mov_b32_e32 v201, v145
	v_pk_mul_f32 v[152:153], v[152:153], v[186:187] op_sel_hi:[1,0]
	v_pk_mul_f32 v[158:159], v[148:149], v[154:155] op_sel:[1,1] op_sel_hi:[0,1]
	v_pk_mul_f32 v[144:145], v[176:177], v[200:201]
	v_pk_fma_f32 v[200:201], v[148:149], v[154:155], v[158:159] op_sel_hi:[1,0,1] neg_lo:[0,0,1] neg_hi:[0,0,1]
	v_pk_fma_f32 v[148:149], v[148:149], v[154:155], v[158:159] op_sel_hi:[1,0,1]
	v_pk_mul_f32 v[154:155], v[150:151], v[152:153] op_sel:[1,1] op_sel_hi:[0,1]
	v_pk_fma_f32 v[158:159], v[150:151], v[152:153], v[154:155] op_sel_hi:[1,0,1] neg_lo:[0,0,1] neg_hi:[0,0,1]
	v_pk_fma_f32 v[150:151], v[150:151], v[152:153], v[154:155] op_sel_hi:[1,0,1]
	v_mov_b32_e32 v201, v149
	v_mov_b32_e32 v159, v151
	v_pk_mul_f32 v[152:153], v[106:107], v[134:135]
	v_pk_mul_f32 v[154:155], v[104:105], v[132:133]
	v_pk_mul_f32 v[150:151], v[190:191], v[158:159]
	v_pk_mul_f32 v[148:149], v[176:177], v[200:201]
	v_pk_mul_f32 v[200:201], v[152:153], v[186:187] op_sel_hi:[1,0]
	v_pk_mul_f32 v[202:203], v[154:155], v[186:187] op_sel_hi:[1,0]
	v_mov_b64_e32 v[152:153], v[234:235]
	v_mov_b64_e32 v[154:155], v[236:237]
	v_mov_b64_e32 v[156:157], v[238:239]
	v_mov_b64_e32 v[158:159], v[240:241]
	v_pk_mul_f32 v[204:205], v[156:157], v[202:203] op_sel:[1,1] op_sel_hi:[0,1]
	v_pk_fma_f32 v[206:207], v[156:157], v[202:203], v[204:205] op_sel_hi:[1,0,1] neg_lo:[0,0,1] neg_hi:[0,0,1]
	v_pk_fma_f32 v[156:157], v[156:157], v[202:203], v[204:205] op_sel_hi:[1,0,1]
	v_pk_mul_f32 v[202:203], v[158:159], v[200:201] op_sel:[1,1] op_sel_hi:[0,1]
	v_pk_fma_f32 v[204:205], v[158:159], v[200:201], v[202:203] op_sel_hi:[1,0,1] neg_lo:[0,0,1] neg_hi:[0,0,1]
	v_pk_fma_f32 v[158:159], v[158:159], v[200:201], v[202:203] op_sel_hi:[1,0,1]
	v_pk_mul_f32 v[200:201], v[78:79], v[130:131]
	v_pk_mul_f32 v[202:203], v[76:77], v[128:129]
	v_pk_mul_f32 v[200:201], v[200:201], v[186:187] op_sel_hi:[1,0]
	v_pk_mul_f32 v[186:187], v[202:203], v[186:187] op_sel_hi:[1,0]
	v_mov_b32_e32 v205, v159
	v_pk_mul_f32 v[202:203], v[152:153], v[186:187] op_sel:[1,1] op_sel_hi:[0,1]
	v_pk_mul_f32 v[158:159], v[190:191], v[204:205]
	v_pk_fma_f32 v[204:205], v[152:153], v[186:187], v[202:203] op_sel_hi:[1,0,1] neg_lo:[0,0,1] neg_hi:[0,0,1]
	v_pk_fma_f32 v[152:153], v[152:153], v[186:187], v[202:203] op_sel_hi:[1,0,1]
	v_pk_mul_f32 v[186:187], v[154:155], v[200:201] op_sel:[1,1] op_sel_hi:[0,1]
	v_pk_fma_f32 v[202:203], v[154:155], v[200:201], v[186:187] op_sel_hi:[1,0,1] neg_lo:[0,0,1] neg_hi:[0,0,1]
	v_pk_fma_f32 v[154:155], v[154:155], v[200:201], v[186:187] op_sel_hi:[1,0,1]
	v_mov_b32_e32 v207, v157
	v_mov_b32_e32 v203, v155
	v_mov_b32_e32 v205, v153
	v_pk_mul_f32 v[156:157], v[176:177], v[206:207]
	v_pk_mul_f32 v[154:155], v[190:191], v[202:203]
	v_pk_mul_f32 v[152:153], v[176:177], v[204:205]
.LBB0_277:
	v_mov_b64_e32 v[186:187], s[24:25]
	v_mad_i64_i32 v[184:185], s[62:63], v184, s64, v[186:187]
	v_lshl_add_u64 v[184:185], v[184:185], 0, s[56:57]
	v_lshl_add_u64 v[184:185], v[184:185], 0, s[78:79]
	v_lshl_add_u64 v[184:185], v[178:179], 1, v[184:185]
	v_cvt_pk_bf16_f32 v144, v144, v145
	v_cvt_pk_bf16_f32 v145, v146, v147
	v_cvt_pk_bf16_f32 v146, v148, v149
	v_cvt_pk_bf16_f32 v147, v150, v151
	global_store_dwordx4 v[184:185], v[144:147], off
	v_mov_b64_e32 v[150:151], v[66:67]
	s_and_b64 vcc, exec, s[4:5]
	v_cvt_pk_bf16_f32 v144, v156, v157
	v_cvt_pk_bf16_f32 v145, v158, v159
	v_cvt_pk_bf16_f32 v146, v152, v153
	v_cvt_pk_bf16_f32 v147, v154, v155
	global_store_dwordx4 v[184:185], v[144:147], off offset:64
	v_add_u32_e32 v184, 48, v180
	v_mov_b64_e32 v[154:155], v[70:71]
	v_mov_b64_e32 v[158:159], v[94:95]
	v_mov_b64_e32 v[146:147], v[102:103]
	v_ashrrev_i32_e32 v185, 31, v184
	v_mov_b64_e32 v[152:153], v[68:69]
	v_mov_b64_e32 v[156:157], v[92:93]
	v_mov_b64_e32 v[148:149], v[64:65]
	v_mov_b64_e32 v[144:145], v[100:101]
	s_cbranch_vccnz .LBB0_279
; __device__ __forceinline__ unsigned cvt_pk_bf16(float lo, float hi) { f32x2_c v = {lo, hi}; bf16x2_c b = __builtin_convertvector(v, bf16x2_c); return __builtin_bit_cast(unsigned, b); }
;     __device__ __forceinline__ void operator()(const f32x4 (&acc)[2][2][4][2], const Unit& u, int wr, int wc, int fr, int fq) const {
;     ...
;                 for (int m = 0; m < 4; ++m) { const int row = row0 + ai * HALF + m * 16; bf16_t* rowp = PROJ + (size_t)row * PP + pn * 256 + 64 * wc + 8 * fq;
;                     f32x4 v[2][2];
; #pragma unroll
;                     for (int bj = 0; bj < 2; ++bj)
; #pragma unroll
;                         for (int n = 0; n < 2; ++n) v[bj][n] = acc[ai][bj][m][n];
;                     if (nrm) {
;                         float ss = 0.f;
; #pragma unroll
;                         for (int bj = 0; bj < 2; ++bj)
; #pragma unroll
;                             for (int n = 0; n < 2; ++n) ss += v[bj][n][0] * v[bj][n][0] + v[bj][n][1] * v[bj][n][1] + v[bj][n][2] * v[bj][n][2] + v[bj][n][3] * v[bj][n][3];
;                         ss += __shfl_xor(ss, 16); ss += __shfl_xor(ss, 32);
;                         const float rinv = __builtin_amdgcn_rsqf(ss * (1.f / 64.f) + EPS);
; #pragma unroll
;                         for (int bj = 0; bj < 2; ++bj)
; #pragma unroll
;                             for (int n = 0; n < 2; ++n) { const f32x4 x = v[bj][n] * wv[bj][n] * rinv; const f32x4 cs = *(const f32x4*)(CS + ((size_t)row * 32 + 16 * bj + 4 * fq + 2 * n) * 2);
;                                 f32x4 o; o[0] = x[0] * cs[0] - x[1] * cs[1]; o[1] = x[0] * cs[1] + x[1] * cs[0]; o[2] = x[2] * cs[2] - x[3] * cs[3]; o[3] = x[2] * cs[3] + x[3] * cs[2]; v[bj][n] = o * sc; }
;                     }
; #pragma unroll
;                     for (int bj = 0; bj < 2; ++bj) { u32x4 w; w.x = cvt_pk_bf16(v[bj][0][0], v[bj][0][1]); w.y = cvt_pk_bf16(v[bj][0][2], v[bj][0][3]); w.z = cvt_pk_bf16(v[bj][1][0], v[bj][1][1]); w.w = cvt_pk_bf16(v[bj][1][2], v[bj][1][3]);
;                         *(u32x4*)(rowp + 32 * bj) = w; } }
	v_mov_b32_e32 v146, v101
	v_mov_b32_e32 v147, v65
	v_mov_b32_e32 v144, v100
	v_mov_b32_e32 v145, v64
	v_pk_mul_f32 v[146:147], v[146:147], v[146:147]
	v_mov_b32_e32 v148, v93
	v_pk_fma_f32 v[144:145], v[144:145], v[144:145], v[146:147]
	v_mov_b32_e32 v146, v102
	v_mov_b32_e32 v147, v66
	v_pk_fma_f32 v[144:145], v[146:147], v[146:147], v[144:145]
	v_mov_b32_e32 v146, v103
	v_mov_b32_e32 v147, v67
	v_mov_b32_e32 v149, v69
	v_pk_fma_f32 v[144:145], v[146:147], v[146:147], v[144:145]
	v_mov_b32_e32 v146, v92
	v_mov_b32_e32 v147, v68
	v_pk_mul_f32 v[148:149], v[148:149], v[148:149]
	v_add_f32_e32 v144, v144, v145
	v_pk_fma_f32 v[146:147], v[146:147], v[146:147], v[148:149]
	v_mov_b32_e32 v148, v94
	v_mov_b32_e32 v149, v70
	v_pk_fma_f32 v[146:147], v[148:149], v[148:149], v[146:147]
	v_mov_b32_e32 v148, v95
	v_mov_b32_e32 v149, v71
	v_pk_fma_f32 v[146:147], v[148:149], v[148:149], v[146:147]
	v_mov_b32_e32 v190, v176
	v_add_f32_e32 v144, v144, v146
	v_add_f32_e32 v144, v144, v147
	ds_bpermute_b32 v145, v196, v144
	v_pk_mul_f32 v[146:147], v[100:101], v[140:141]
	v_mov_b32_e32 v191, v176
	s_waitcnt lgkmcnt(0)
	v_add_f32_e32 v144, v144, v145
	ds_bpermute_b32 v145, v197, v144
	s_waitcnt lgkmcnt(0)
	v_add_f32_e32 v144, v144, v145
	v_fmamk_f32 v144, v144, 0x3c800000, v253
	v_rsq_f32_e32 v186, v144
	v_pk_mul_f32 v[144:145], v[102:103], v[142:143]
	v_pk_mul_f32 v[154:155], v[146:147], v[186:187] op_sel_hi:[1,0]
	v_pk_mul_f32 v[152:153], v[144:145], v[186:187] op_sel_hi:[1,0]
	v_lshlrev_b64 v[144:145], 8, v[184:185]
	v_lshl_add_u64 v[144:145], s[22:23], 0, v[144:145]
	v_lshl_add_u64 v[156:157], v[182:183], 3, v[144:145]
	s_waitcnt vmcnt(2)
	v_mov_b64_e32 v[148:149], v[208:209]
	v_mov_b64_e32 v[150:151], v[210:211]
	v_mov_b64_e32 v[144:145], v[212:213]
	v_mov_b64_e32 v[146:147], v[214:215]
	v_lshl_add_u64 v[248:249], v[156:157], 0, s[100:101]
	global_load_dwordx4 v[224:227], v[248:249], off offset:16
	global_load_dwordx4 v[228:231], v[248:249], off
	global_load_dwordx4 v[234:237], v[248:249], off offset:144
	global_load_dwordx4 v[238:241], v[248:249], off offset:128
	v_pk_mul_f32 v[158:159], v[144:145], v[154:155] op_sel:[1,1] op_sel_hi:[0,1]
	v_pk_fma_f32 v[200:201], v[144:145], v[154:155], v[158:159] op_sel_hi:[1,0,1] neg_lo:[0,0,1] neg_hi:[0,0,1]
	v_pk_fma_f32 v[144:145], v[144:145], v[154:155], v[158:159] op_sel_hi:[1,0,1]
	v_pk_mul_f32 v[154:155], v[146:147], v[152:153] op_sel:[1,1] op_sel_hi:[0,1]
	v_pk_fma_f32 v[158:159], v[146:147], v[152:153], v[154:155] op_sel_hi:[1,0,1] neg_lo:[0,0,1] neg_hi:[0,0,1]
	v_pk_fma_f32 v[146:147], v[146:147], v[152:153], v[154:155] op_sel_hi:[1,0,1]
	v_pk_mul_f32 v[154:155], v[64:65], v[136:137]
	v_mov_b32_e32 v159, v147
	v_pk_mul_f32 v[152:153], v[66:67], v[138:139]
	v_pk_mul_f32 v[154:155], v[154:155], v[186:187] op_sel_hi:[1,0]
	v_pk_mul_f32 v[146:147], v[190:191], v[158:159]
	v_mov_b32_e32 v201, v145
	v_pk_mul_f32 v[152:153], v[152:153], v[186:187] op_sel_hi:[1,0]
	v_pk_mul_f32 v[158:159], v[148:149], v[154:155] op_sel:[1,1] op_sel_hi:[0,1]
	v_pk_mul_f32 v[144:145], v[176:177], v[200:201]
	v_pk_fma_f32 v[200:201], v[148:149], v[154:155], v[158:159] op_sel_hi:[1,0,1] neg_lo:[0,0,1] neg_hi:[0,0,1]
	v_pk_fma_f32 v[148:149], v[148:149], v[154:155], v[158:159] op_sel_hi:[1,0,1]
	v_pk_mul_f32 v[154:155], v[150:151], v[152:153] op_sel:[1,1] op_sel_hi:[0,1]
	v_pk_fma_f32 v[158:159], v[150:151], v[152:153], v[154:155] op_sel_hi:[1,0,1] neg_lo:[0,0,1] neg_hi:[0,0,1]
	v_pk_fma_f32 v[150:151], v[150:151], v[152:153], v[154:155] op_sel_hi:[1,0,1]
	v_mov_b32_e32 v201, v149
	v_mov_b32_e32 v159, v151
	v_pk_mul_f32 v[152:153], v[94:95], v[134:135]
	v_pk_mul_f32 v[154:155], v[92:93], v[132:133]
	v_pk_mul_f32 v[150:151], v[190:191], v[158:159]
	v_pk_mul_f32 v[148:149], v[176:177], v[200:201]
	v_pk_mul_f32 v[200:201], v[152:153], v[186:187] op_sel_hi:[1,0]
	v_pk_mul_f32 v[202:203], v[154:155], v[186:187] op_sel_hi:[1,0]
	v_mov_b64_e32 v[152:153], v[216:217]
	v_mov_b64_e32 v[154:155], v[218:219]
	v_mov_b64_e32 v[156:157], v[220:221]
	v_mov_b64_e32 v[158:159], v[222:223]
	v_pk_mul_f32 v[204:205], v[156:157], v[202:203] op_sel:[1,1] op_sel_hi:[0,1]
	v_pk_fma_f32 v[206:207], v[156:157], v[202:203], v[204:205] op_sel_hi:[1,0,1] neg_lo:[0,0,1] neg_hi:[0,0,1]
	v_pk_fma_f32 v[156:157], v[156:157], v[202:203], v[204:205] op_sel_hi:[1,0,1]
	v_pk_mul_f32 v[202:203], v[158:159], v[200:201] op_sel:[1,1] op_sel_hi:[0,1]
	v_pk_fma_f32 v[204:205], v[158:159], v[200:201], v[202:203] op_sel_hi:[1,0,1] neg_lo:[0,0,1] neg_hi:[0,0,1]
	v_pk_fma_f32 v[158:159], v[158:159], v[200:201], v[202:203] op_sel_hi:[1,0,1]
	v_pk_mul_f32 v[200:201], v[70:71], v[130:131]
	v_pk_mul_f32 v[202:203], v[68:69], v[128:129]
	v_pk_mul_f32 v[200:201], v[200:201], v[186:187] op_sel_hi:[1,0]
	v_pk_mul_f32 v[186:187], v[202:203], v[186:187] op_sel_hi:[1,0]
	v_mov_b32_e32 v205, v159
	v_pk_mul_f32 v[202:203], v[152:153], v[186:187] op_sel:[1,1] op_sel_hi:[0,1]
	v_pk_mul_f32 v[158:159], v[190:191], v[204:205]
	v_pk_fma_f32 v[204:205], v[152:153], v[186:187], v[202:203] op_sel_hi:[1,0,1] neg_lo:[0,0,1] neg_hi:[0,0,1]
	v_pk_fma_f32 v[152:153], v[152:153], v[186:187], v[202:203] op_sel_hi:[1,0,1]
	v_pk_mul_f32 v[186:187], v[154:155], v[200:201] op_sel:[1,1] op_sel_hi:[0,1]
	v_pk_fma_f32 v[202:203], v[154:155], v[200:201], v[186:187] op_sel_hi:[1,0,1] neg_lo:[0,0,1] neg_hi:[0,0,1]
	v_pk_fma_f32 v[154:155], v[154:155], v[200:201], v[186:187] op_sel_hi:[1,0,1]
	v_mov_b32_e32 v207, v157
	v_mov_b32_e32 v203, v155
	v_mov_b32_e32 v205, v153
	v_pk_mul_f32 v[156:157], v[176:177], v[206:207]
	v_pk_mul_f32 v[154:155], v[190:191], v[202:203]
	v_pk_mul_f32 v[152:153], v[176:177], v[204:205]
; __device__ __forceinline__ unsigned cvt_pk_bf16(float lo, float hi) { f32x2_c v = {lo, hi}; bf16x2_c b = __builtin_convertvector(v, bf16x2_c); return __builtin_bit_cast(unsigned, b); }
;     __device__ __forceinline__ void operator()(const f32x4 (&acc)[2][2][4][2], const Unit& u, int wr, int wc, int fr, int fq) const {
;     ...
;                 for (int m = 0; m < 4; ++m) { const int row = row0 + ai * HALF + m * 16; bf16_t* rowp = PROJ + (size_t)row * PP + pn * 256 + 64 * wc + 8 * fq;
;                     f32x4 v[2][2];
; #pragma unroll
;                     for (int bj = 0; bj < 2; ++bj)
; #pragma unroll
;                         for (int n = 0; n < 2; ++n) v[bj][n] = acc[ai][bj][m][n];
;                     if (nrm) {
;                         float ss = 0.f;
; #pragma unroll
;                         for (int bj = 0; bj < 2; ++bj)
; #pragma unroll
;                             for (int n = 0; n < 2; ++n) ss += v[bj][n][0] * v[bj][n][0] + v[bj][n][1] * v[bj][n][1] + v[bj][n][2] * v[bj][n][2] + v[bj][n][3] * v[bj][n][3];
;                         ss += __shfl_xor(ss, 16); ss += __shfl_xor(ss, 32);
;                         const float rinv = __builtin_amdgcn_rsqf(ss * (1.f / 64.f) + EPS);
; #pragma unroll
;                         for (int bj = 0; bj < 2; ++bj)
; #pragma unroll
;                             for (int n = 0; n < 2; ++n) { const f32x4 x = v[bj][n] * wv[bj][n] * rinv; const f32x4 cs = *(const f32x4*)(CS + ((size_t)row * 32 + 16 * bj + 4 * fq + 2 * n) * 2);
;                                 f32x4 o; o[0] = x[0] * cs[0] - x[1] * cs[1]; o[1] = x[0] * cs[1] + x[1] * cs[0]; o[2] = x[2] * cs[2] - x[3] * cs[3]; o[3] = x[2] * cs[3] + x[3] * cs[2]; v[bj][n] = o * sc; }
;                     }
; #pragma unroll
;                     for (int bj = 0; bj < 2; ++bj) { u32x4 w; w.x = cvt_pk_bf16(v[bj][0][0], v[bj][0][1]); w.y = cvt_pk_bf16(v[bj][0][2], v[bj][0][3]); w.z = cvt_pk_bf16(v[bj][1][0], v[bj][1][1]); w.w = cvt_pk_bf16(v[bj][1][2], v[bj][1][3]);
;                         *(u32x4*)(rowp + 32 * bj) = w; } }
.LBB0_279:
	v_mov_b64_e32 v[186:187], s[24:25]
	v_mad_i64_i32 v[184:185], s[62:63], v184, s64, v[186:187]
	s_mov_b32 s57, s79
	v_lshl_add_u64 v[184:185], v[184:185], 0, s[56:57]
	v_lshl_add_u64 v[184:185], v[184:185], 0, s[78:79]
	v_lshl_add_u64 v[184:185], v[178:179], 1, v[184:185]
	v_cvt_pk_bf16_f32 v144, v144, v145
	v_cvt_pk_bf16_f32 v145, v146, v147
	v_cvt_pk_bf16_f32 v146, v148, v149
	v_cvt_pk_bf16_f32 v147, v150, v151
	global_store_dwordx4 v[184:185], v[144:147], off
	v_mov_b64_e32 v[150:151], v[38:39]
	s_and_b64 vcc, exec, s[4:5]
	v_cvt_pk_bf16_f32 v144, v156, v157
	v_cvt_pk_bf16_f32 v145, v158, v159
	v_cvt_pk_bf16_f32 v146, v152, v153
	v_cvt_pk_bf16_f32 v147, v154, v155
	global_store_dwordx4 v[184:185], v[144:147], off offset:64
	v_add_u32_e32 v184, 0x80, v180
	v_mov_b64_e32 v[154:155], v[46:47]
	v_mov_b64_e32 v[158:159], v[58:59]
	v_mov_b64_e32 v[146:147], v[62:63]
	v_ashrrev_i32_e32 v185, 31, v184
	v_mov_b64_e32 v[152:153], v[44:45]
	v_mov_b64_e32 v[156:157], v[56:57]
	v_mov_b64_e32 v[148:149], v[36:37]
	v_mov_b64_e32 v[144:145], v[60:61]
	s_cbranch_vccnz .LBB0_281
	v_mov_b32_e32 v146, v61
	v_mov_b32_e32 v147, v37
	v_mov_b32_e32 v144, v60
	v_mov_b32_e32 v145, v36
	v_pk_mul_f32 v[146:147], v[146:147], v[146:147]
	v_mov_b32_e32 v148, v57
	v_pk_fma_f32 v[144:145], v[144:145], v[144:145], v[146:147]
	v_mov_b32_e32 v146, v62
	v_mov_b32_e32 v147, v38
	v_pk_fma_f32 v[144:145], v[146:147], v[146:147], v[144:145]
	v_mov_b32_e32 v146, v63
	v_mov_b32_e32 v147, v39
	v_mov_b32_e32 v149, v45
	v_pk_fma_f32 v[144:145], v[146:147], v[146:147], v[144:145]
	v_mov_b32_e32 v146, v56
	v_mov_b32_e32 v147, v44
	v_pk_mul_f32 v[148:149], v[148:149], v[148:149]
	v_add_f32_e32 v144, v144, v145
	v_pk_fma_f32 v[146:147], v[146:147], v[146:147], v[148:149]
	v_mov_b32_e32 v148, v58
	v_mov_b32_e32 v149, v46
	v_pk_fma_f32 v[146:147], v[148:149], v[148:149], v[146:147]
	v_mov_b32_e32 v148, v59
	v_mov_b32_e32 v149, v47
	v_pk_fma_f32 v[146:147], v[148:149], v[148:149], v[146:147]
	v_mov_b32_e32 v190, v176
	v_add_f32_e32 v144, v144, v146
	v_add_f32_e32 v144, v144, v147
	ds_bpermute_b32 v145, v196, v144
	v_pk_mul_f32 v[146:147], v[60:61], v[140:141]
	v_mov_b32_e32 v191, v176
	s_waitcnt lgkmcnt(0)
	v_add_f32_e32 v144, v144, v145
	ds_bpermute_b32 v145, v197, v144
	s_waitcnt lgkmcnt(0)
	v_add_f32_e32 v144, v144, v145
	v_fmamk_f32 v144, v144, 0x3c800000, v253
	v_rsq_f32_e32 v186, v144
	v_pk_mul_f32 v[144:145], v[62:63], v[142:143]
	v_pk_mul_f32 v[154:155], v[146:147], v[186:187] op_sel_hi:[1,0]
	v_pk_mul_f32 v[152:153], v[144:145], v[186:187] op_sel_hi:[1,0]
	v_lshlrev_b64 v[144:145], 8, v[184:185]
	v_lshl_add_u64 v[144:145], s[22:23], 0, v[144:145]
	v_lshl_add_u64 v[156:157], v[182:183], 3, v[144:145]
	s_waitcnt vmcnt(2)
	v_mov_b64_e32 v[148:149], v[224:225]
	v_mov_b64_e32 v[150:151], v[226:227]
	v_mov_b64_e32 v[144:145], v[228:229]
	v_mov_b64_e32 v[146:147], v[230:231]
	v_lshl_add_u64 v[248:249], v[156:157], 0, s[98:99]
	global_load_dwordx4 v[208:211], v[248:249], off offset:16
	global_load_dwordx4 v[212:215], v[248:249], off
	global_load_dwordx4 v[216:219], v[248:249], off offset:144
	global_load_dwordx4 v[220:223], v[248:249], off offset:128
	v_pk_mul_f32 v[158:159], v[144:145], v[154:155] op_sel:[1,1] op_sel_hi:[0,1]
	v_pk_fma_f32 v[200:201], v[144:145], v[154:155], v[158:159] op_sel_hi:[1,0,1] neg_lo:[0,0,1] neg_hi:[0,0,1]
	v_pk_fma_f32 v[144:145], v[144:145], v[154:155], v[158:159] op_sel_hi:[1,0,1]
	v_pk_mul_f32 v[154:155], v[146:147], v[152:153] op_sel:[1,1] op_sel_hi:[0,1]
	v_pk_fma_f32 v[158:159], v[146:147], v[152:153], v[154:155] op_sel_hi:[1,0,1] neg_lo:[0,0,1] neg_hi:[0,0,1]
	v_pk_fma_f32 v[146:147], v[146:147], v[152:153], v[154:155] op_sel_hi:[1,0,1]
	v_pk_mul_f32 v[154:155], v[36:37], v[136:137]
	v_mov_b32_e32 v159, v147
	v_pk_mul_f32 v[152:153], v[38:39], v[138:139]
	v_pk_mul_f32 v[154:155], v[154:155], v[186:187] op_sel_hi:[1,0]
	v_pk_mul_f32 v[146:147], v[190:191], v[158:159]
	v_mov_b32_e32 v201, v145
	v_pk_mul_f32 v[152:153], v[152:153], v[186:187] op_sel_hi:[1,0]
	v_pk_mul_f32 v[158:159], v[148:149], v[154:155] op_sel:[1,1] op_sel_hi:[0,1]
	v_pk_mul_f32 v[144:145], v[176:177], v[200:201]
	v_pk_fma_f32 v[200:201], v[148:149], v[154:155], v[158:159] op_sel_hi:[1,0,1] neg_lo:[0,0,1] neg_hi:[0,0,1]
	v_pk_fma_f32 v[148:149], v[148:149], v[154:155], v[158:159] op_sel_hi:[1,0,1]
	v_pk_mul_f32 v[154:155], v[150:151], v[152:153] op_sel:[1,1] op_sel_hi:[0,1]
	v_pk_fma_f32 v[158:159], v[150:151], v[152:153], v[154:155] op_sel_hi:[1,0,1] neg_lo:[0,0,1] neg_hi:[0,0,1]
	v_pk_fma_f32 v[150:151], v[150:151], v[152:153], v[154:155] op_sel_hi:[1,0,1]
	v_mov_b32_e32 v201, v149
	v_mov_b32_e32 v159, v151
	v_pk_mul_f32 v[152:153], v[58:59], v[134:135]
	v_pk_mul_f32 v[154:155], v[56:57], v[132:133]
	v_pk_mul_f32 v[150:151], v[190:191], v[158:159]
	v_pk_mul_f32 v[148:149], v[176:177], v[200:201]
	v_pk_mul_f32 v[200:201], v[152:153], v[186:187] op_sel_hi:[1,0]
	v_pk_mul_f32 v[202:203], v[154:155], v[186:187] op_sel_hi:[1,0]
	v_mov_b64_e32 v[152:153], v[234:235]
	v_mov_b64_e32 v[154:155], v[236:237]
	v_mov_b64_e32 v[156:157], v[238:239]
	v_mov_b64_e32 v[158:159], v[240:241]
	v_pk_mul_f32 v[204:205], v[156:157], v[202:203] op_sel:[1,1] op_sel_hi:[0,1]
	v_pk_fma_f32 v[206:207], v[156:157], v[202:203], v[204:205] op_sel_hi:[1,0,1] neg_lo:[0,0,1] neg_hi:[0,0,1]
	v_pk_fma_f32 v[156:157], v[156:157], v[202:203], v[204:205] op_sel_hi:[1,0,1]
	v_pk_mul_f32 v[202:203], v[158:159], v[200:201] op_sel:[1,1] op_sel_hi:[0,1]
	v_pk_fma_f32 v[204:205], v[158:159], v[200:201], v[202:203] op_sel_hi:[1,0,1] neg_lo:[0,0,1] neg_hi:[0,0,1]
	v_pk_fma_f32 v[158:159], v[158:159], v[200:201], v[202:203] op_sel_hi:[1,0,1]
	v_pk_mul_f32 v[200:201], v[46:47], v[130:131]
	v_pk_mul_f32 v[202:203], v[44:45], v[128:129]
	v_pk_mul_f32 v[200:201], v[200:201], v[186:187] op_sel_hi:[1,0]
	v_pk_mul_f32 v[186:187], v[202:203], v[186:187] op_sel_hi:[1,0]
	v_mov_b32_e32 v205, v159
	v_pk_mul_f32 v[202:203], v[152:153], v[186:187] op_sel:[1,1] op_sel_hi:[0,1]
	v_pk_mul_f32 v[158:159], v[190:191], v[204:205]
	v_pk_fma_f32 v[204:205], v[152:153], v[186:187], v[202:203] op_sel_hi:[1,0,1] neg_lo:[0,0,1] neg_hi:[0,0,1]
	v_pk_fma_f32 v[152:153], v[152:153], v[186:187], v[202:203] op_sel_hi:[1,0,1]
	v_pk_mul_f32 v[186:187], v[154:155], v[200:201] op_sel:[1,1] op_sel_hi:[0,1]
	v_pk_fma_f32 v[202:203], v[154:155], v[200:201], v[186:187] op_sel_hi:[1,0,1] neg_lo:[0,0,1] neg_hi:[0,0,1]
	v_pk_fma_f32 v[154:155], v[154:155], v[200:201], v[186:187] op_sel_hi:[1,0,1]
	v_mov_b32_e32 v207, v157
	v_mov_b32_e32 v203, v155
	v_mov_b32_e32 v205, v153
	v_pk_mul_f32 v[156:157], v[176:177], v[206:207]
	v_pk_mul_f32 v[154:155], v[190:191], v[202:203]
	v_pk_mul_f32 v[152:153], v[176:177], v[204:205]
; __device__ __forceinline__ unsigned cvt_pk_bf16(float lo, float hi) { f32x2_c v = {lo, hi}; bf16x2_c b = __builtin_convertvector(v, bf16x2_c); return __builtin_bit_cast(unsigned, b); }
;     __device__ __forceinline__ void operator()(const f32x4 (&acc)[2][2][4][2], const Unit& u, int wr, int wc, int fr, int fq) const {
;     ...
;                 for (int m = 0; m < 4; ++m) { const int row = row0 + ai * HALF + m * 16; bf16_t* rowp = PROJ + (size_t)row * PP + pn * 256 + 64 * wc + 8 * fq;
;                     f32x4 v[2][2];
; #pragma unroll
;                     for (int bj = 0; bj < 2; ++bj)
; #pragma unroll
;                         for (int n = 0; n < 2; ++n) v[bj][n] = acc[ai][bj][m][n];
;                     if (nrm) {
;                         float ss = 0.f;
; #pragma unroll
;                         for (int bj = 0; bj < 2; ++bj)
; #pragma unroll
;                             for (int n = 0; n < 2; ++n) ss += v[bj][n][0] * v[bj][n][0] + v[bj][n][1] * v[bj][n][1] + v[bj][n][2] * v[bj][n][2] + v[bj][n][3] * v[bj][n][3];
;                         ss += __shfl_xor(ss, 16); ss += __shfl_xor(ss, 32);
;                         const float rinv = __builtin_amdgcn_rsqf(ss * (1.f / 64.f) + EPS);
; #pragma unroll
;                         for (int bj = 0; bj < 2; ++bj)
; #pragma unroll
;                             for (int n = 0; n < 2; ++n) { const f32x4 x = v[bj][n] * wv[bj][n] * rinv; const f32x4 cs = *(const f32x4*)(CS + ((size_t)row * 32 + 16 * bj + 4 * fq + 2 * n) * 2);
;                                 f32x4 o; o[0] = x[0] * cs[0] - x[1] * cs[1]; o[1] = x[0] * cs[1] + x[1] * cs[0]; o[2] = x[2] * cs[2] - x[3] * cs[3]; o[3] = x[2] * cs[3] + x[3] * cs[2]; v[bj][n] = o * sc; }
;                     }
; #pragma unroll
;                     for (int bj = 0; bj < 2; ++bj) { u32x4 w; w.x = cvt_pk_bf16(v[bj][0][0], v[bj][0][1]); w.y = cvt_pk_bf16(v[bj][0][2], v[bj][0][3]); w.z = cvt_pk_bf16(v[bj][1][0], v[bj][1][1]); w.w = cvt_pk_bf16(v[bj][1][2], v[bj][1][3]);
;                         *(u32x4*)(rowp + 32 * bj) = w; } }
.LBB0_281:
	v_mov_b64_e32 v[186:187], s[24:25]
	v_mad_i64_i32 v[184:185], s[62:63], v184, s64, v[186:187]
	v_lshl_add_u64 v[184:185], v[184:185], 0, s[56:57]
	v_lshl_add_u64 v[184:185], v[184:185], 0, s[78:79]
	v_lshl_add_u64 v[184:185], v[178:179], 1, v[184:185]
	v_cvt_pk_bf16_f32 v144, v144, v145
	v_cvt_pk_bf16_f32 v145, v146, v147
	v_cvt_pk_bf16_f32 v146, v148, v149
	v_cvt_pk_bf16_f32 v147, v150, v151
	global_store_dwordx4 v[184:185], v[144:147], off
	v_mov_b64_e32 v[150:151], v[26:27]
	s_and_b64 vcc, exec, s[4:5]
	v_cvt_pk_bf16_f32 v144, v156, v157
	v_cvt_pk_bf16_f32 v145, v158, v159
	v_cvt_pk_bf16_f32 v146, v152, v153
	v_cvt_pk_bf16_f32 v147, v154, v155
	global_store_dwordx4 v[184:185], v[144:147], off offset:64
	v_add_u32_e32 v184, 0x90, v180
	v_mov_b64_e32 v[154:155], v[34:35]
	v_mov_b64_e32 v[158:159], v[50:51]
	v_mov_b64_e32 v[146:147], v[54:55]
	v_ashrrev_i32_e32 v185, 31, v184
	v_mov_b64_e32 v[152:153], v[32:33]
	v_mov_b64_e32 v[156:157], v[48:49]
	v_mov_b64_e32 v[148:149], v[24:25]
	v_mov_b64_e32 v[144:145], v[52:53]
	s_cbranch_vccnz .LBB0_283
	v_mov_b32_e32 v146, v53
	v_mov_b32_e32 v147, v25
	v_mov_b32_e32 v144, v52
	v_mov_b32_e32 v145, v24
	v_pk_mul_f32 v[146:147], v[146:147], v[146:147]
	v_mov_b32_e32 v148, v49
	v_pk_fma_f32 v[144:145], v[144:145], v[144:145], v[146:147]
	v_mov_b32_e32 v146, v54
	v_mov_b32_e32 v147, v26
	v_pk_fma_f32 v[144:145], v[146:147], v[146:147], v[144:145]
	v_mov_b32_e32 v146, v55
	v_mov_b32_e32 v147, v27
	v_mov_b32_e32 v149, v33
	v_pk_fma_f32 v[144:145], v[146:147], v[146:147], v[144:145]
	v_mov_b32_e32 v146, v48
	v_mov_b32_e32 v147, v32
	v_pk_mul_f32 v[148:149], v[148:149], v[148:149]
	v_add_f32_e32 v144, v144, v145
	v_pk_fma_f32 v[146:147], v[146:147], v[146:147], v[148:149]
	v_mov_b32_e32 v148, v50
	v_mov_b32_e32 v149, v34
	v_pk_fma_f32 v[146:147], v[148:149], v[148:149], v[146:147]
	v_mov_b32_e32 v148, v51
	v_mov_b32_e32 v149, v35
	v_pk_fma_f32 v[146:147], v[148:149], v[148:149], v[146:147]
	v_mov_b32_e32 v190, v176
	v_add_f32_e32 v144, v144, v146
	v_add_f32_e32 v144, v144, v147
	ds_bpermute_b32 v145, v196, v144
	v_pk_mul_f32 v[146:147], v[52:53], v[140:141]
	v_mov_b32_e32 v191, v176
	s_waitcnt lgkmcnt(0)
	v_add_f32_e32 v144, v144, v145
	ds_bpermute_b32 v145, v197, v144
	s_waitcnt lgkmcnt(0)
	v_add_f32_e32 v144, v144, v145
	v_fmamk_f32 v144, v144, 0x3c800000, v253
	v_rsq_f32_e32 v186, v144
	v_pk_mul_f32 v[144:145], v[54:55], v[142:143]
	v_pk_mul_f32 v[154:155], v[146:147], v[186:187] op_sel_hi:[1,0]
	v_pk_mul_f32 v[152:153], v[144:145], v[186:187] op_sel_hi:[1,0]
	v_lshlrev_b64 v[144:145], 8, v[184:185]
	v_lshl_add_u64 v[144:145], s[22:23], 0, v[144:145]
	v_lshl_add_u64 v[156:157], v[182:183], 3, v[144:145]
	s_waitcnt vmcnt(2)
	v_mov_b64_e32 v[148:149], v[208:209]
	v_mov_b64_e32 v[150:151], v[210:211]
	v_mov_b64_e32 v[144:145], v[212:213]
	v_mov_b64_e32 v[146:147], v[214:215]
	v_lshl_add_u64 v[248:249], v[156:157], 0, s[98:99]
	global_load_dwordx4 v[224:227], v[248:249], off offset:16
	global_load_dwordx4 v[228:231], v[248:249], off
	global_load_dwordx4 v[234:237], v[248:249], off offset:144
	global_load_dwordx4 v[238:241], v[248:249], off offset:128
	v_pk_mul_f32 v[158:159], v[144:145], v[154:155] op_sel:[1,1] op_sel_hi:[0,1]
	v_pk_fma_f32 v[200:201], v[144:145], v[154:155], v[158:159] op_sel_hi:[1,0,1] neg_lo:[0,0,1] neg_hi:[0,0,1]
	v_pk_fma_f32 v[144:145], v[144:145], v[154:155], v[158:159] op_sel_hi:[1,0,1]
	v_pk_mul_f32 v[154:155], v[146:147], v[152:153] op_sel:[1,1] op_sel_hi:[0,1]
	v_pk_fma_f32 v[158:159], v[146:147], v[152:153], v[154:155] op_sel_hi:[1,0,1] neg_lo:[0,0,1] neg_hi:[0,0,1]
	v_pk_fma_f32 v[146:147], v[146:147], v[152:153], v[154:155] op_sel_hi:[1,0,1]
	v_pk_mul_f32 v[154:155], v[24:25], v[136:137]
	v_mov_b32_e32 v159, v147
	v_pk_mul_f32 v[152:153], v[26:27], v[138:139]
	v_pk_mul_f32 v[154:155], v[154:155], v[186:187] op_sel_hi:[1,0]
	v_pk_mul_f32 v[146:147], v[190:191], v[158:159]
	v_mov_b32_e32 v201, v145
	v_pk_mul_f32 v[152:153], v[152:153], v[186:187] op_sel_hi:[1,0]
	v_pk_mul_f32 v[158:159], v[148:149], v[154:155] op_sel:[1,1] op_sel_hi:[0,1]
	v_pk_mul_f32 v[144:145], v[176:177], v[200:201]
	v_pk_fma_f32 v[200:201], v[148:149], v[154:155], v[158:159] op_sel_hi:[1,0,1] neg_lo:[0,0,1] neg_hi:[0,0,1]
	v_pk_fma_f32 v[148:149], v[148:149], v[154:155], v[158:159] op_sel_hi:[1,0,1]
	v_pk_mul_f32 v[154:155], v[150:151], v[152:153] op_sel:[1,1] op_sel_hi:[0,1]
	v_pk_fma_f32 v[158:159], v[150:151], v[152:153], v[154:155] op_sel_hi:[1,0,1] neg_lo:[0,0,1] neg_hi:[0,0,1]
	v_pk_fma_f32 v[150:151], v[150:151], v[152:153], v[154:155] op_sel_hi:[1,0,1]
	v_mov_b32_e32 v201, v149
	v_mov_b32_e32 v159, v151
	v_pk_mul_f32 v[152:153], v[50:51], v[134:135]
	v_pk_mul_f32 v[154:155], v[48:49], v[132:133]
	v_pk_mul_f32 v[150:151], v[190:191], v[158:159]
	v_pk_mul_f32 v[148:149], v[176:177], v[200:201]
	v_pk_mul_f32 v[200:201], v[152:153], v[186:187] op_sel_hi:[1,0]
	v_pk_mul_f32 v[202:203], v[154:155], v[186:187] op_sel_hi:[1,0]
	v_mov_b64_e32 v[152:153], v[216:217]
	v_mov_b64_e32 v[154:155], v[218:219]
	v_mov_b64_e32 v[156:157], v[220:221]
	v_mov_b64_e32 v[158:159], v[222:223]
	v_pk_mul_f32 v[204:205], v[156:157], v[202:203] op_sel:[1,1] op_sel_hi:[0,1]
	v_pk_fma_f32 v[206:207], v[156:157], v[202:203], v[204:205] op_sel_hi:[1,0,1] neg_lo:[0,0,1] neg_hi:[0,0,1]
	v_pk_fma_f32 v[156:157], v[156:157], v[202:203], v[204:205] op_sel_hi:[1,0,1]
	v_pk_mul_f32 v[202:203], v[158:159], v[200:201] op_sel:[1,1] op_sel_hi:[0,1]
	v_pk_fma_f32 v[204:205], v[158:159], v[200:201], v[202:203] op_sel_hi:[1,0,1] neg_lo:[0,0,1] neg_hi:[0,0,1]
	v_pk_fma_f32 v[158:159], v[158:159], v[200:201], v[202:203] op_sel_hi:[1,0,1]
	v_pk_mul_f32 v[200:201], v[34:35], v[130:131]
	v_pk_mul_f32 v[202:203], v[32:33], v[128:129]
	v_pk_mul_f32 v[200:201], v[200:201], v[186:187] op_sel_hi:[1,0]
	v_pk_mul_f32 v[186:187], v[202:203], v[186:187] op_sel_hi:[1,0]
	v_mov_b32_e32 v205, v159
	v_pk_mul_f32 v[202:203], v[152:153], v[186:187] op_sel:[1,1] op_sel_hi:[0,1]
	v_pk_mul_f32 v[158:159], v[190:191], v[204:205]
	v_pk_fma_f32 v[204:205], v[152:153], v[186:187], v[202:203] op_sel_hi:[1,0,1] neg_lo:[0,0,1] neg_hi:[0,0,1]
	v_pk_fma_f32 v[152:153], v[152:153], v[186:187], v[202:203] op_sel_hi:[1,0,1]
	v_pk_mul_f32 v[186:187], v[154:155], v[200:201] op_sel:[1,1] op_sel_hi:[0,1]
	v_pk_fma_f32 v[202:203], v[154:155], v[200:201], v[186:187] op_sel_hi:[1,0,1] neg_lo:[0,0,1] neg_hi:[0,0,1]
	v_pk_fma_f32 v[154:155], v[154:155], v[200:201], v[186:187] op_sel_hi:[1,0,1]
	v_mov_b32_e32 v207, v157
	v_mov_b32_e32 v203, v155
	v_mov_b32_e32 v205, v153
	v_pk_mul_f32 v[156:157], v[176:177], v[206:207]
	v_pk_mul_f32 v[154:155], v[190:191], v[202:203]
	v_pk_mul_f32 v[152:153], v[176:177], v[204:205]
; __device__ __forceinline__ unsigned cvt_pk_bf16(float lo, float hi) { f32x2_c v = {lo, hi}; bf16x2_c b = __builtin_convertvector(v, bf16x2_c); return __builtin_bit_cast(unsigned, b); }
;     __device__ __forceinline__ void operator()(const f32x4 (&acc)[2][2][4][2], const Unit& u, int wr, int wc, int fr, int fq) const {
;     ...
;                 for (int m = 0; m < 4; ++m) { const int row = row0 + ai * HALF + m * 16; bf16_t* rowp = PROJ + (size_t)row * PP + pn * 256 + 64 * wc + 8 * fq;
;                     f32x4 v[2][2];
; #pragma unroll
;                     for (int bj = 0; bj < 2; ++bj)
; #pragma unroll
;                         for (int n = 0; n < 2; ++n) v[bj][n] = acc[ai][bj][m][n];
;                     if (nrm) {
;                         float ss = 0.f;
; #pragma unroll
;                         for (int bj = 0; bj < 2; ++bj)
; #pragma unroll
;                             for (int n = 0; n < 2; ++n) ss += v[bj][n][0] * v[bj][n][0] + v[bj][n][1] * v[bj][n][1] + v[bj][n][2] * v[bj][n][2] + v[bj][n][3] * v[bj][n][3];
;                         ss += __shfl_xor(ss, 16); ss += __shfl_xor(ss, 32);
;                         const float rinv = __builtin_amdgcn_rsqf(ss * (1.f / 64.f) + EPS);
; #pragma unroll
;                         for (int bj = 0; bj < 2; ++bj)
; #pragma unroll
;                             for (int n = 0; n < 2; ++n) { const f32x4 x = v[bj][n] * wv[bj][n] * rinv; const f32x4 cs = *(const f32x4*)(CS + ((size_t)row * 32 + 16 * bj + 4 * fq + 2 * n) * 2);
;                                 f32x4 o; o[0] = x[0] * cs[0] - x[1] * cs[1]; o[1] = x[0] * cs[1] + x[1] * cs[0]; o[2] = x[2] * cs[2] - x[3] * cs[3]; o[3] = x[2] * cs[3] + x[3] * cs[2]; v[bj][n] = o * sc; }
;                     }
; #pragma unroll
;                     for (int bj = 0; bj < 2; ++bj) { u32x4 w; w.x = cvt_pk_bf16(v[bj][0][0], v[bj][0][1]); w.y = cvt_pk_bf16(v[bj][0][2], v[bj][0][3]); w.z = cvt_pk_bf16(v[bj][1][0], v[bj][1][1]); w.w = cvt_pk_bf16(v[bj][1][2], v[bj][1][3]);
;                         *(u32x4*)(rowp + 32 * bj) = w; } }
.LBB0_283:
	v_mov_b64_e32 v[186:187], s[24:25]
	v_mad_i64_i32 v[184:185], s[62:63], v184, s64, v[186:187]
	s_mov_b32 s57, s79
	v_lshl_add_u64 v[184:185], v[184:185], 0, s[56:57]
	v_lshl_add_u64 v[184:185], v[184:185], 0, s[78:79]
	v_lshl_add_u64 v[184:185], v[178:179], 1, v[184:185]
	v_cvt_pk_bf16_f32 v144, v144, v145
	v_cvt_pk_bf16_f32 v145, v146, v147
	v_cvt_pk_bf16_f32 v146, v148, v149
	v_cvt_pk_bf16_f32 v147, v150, v151
	global_store_dwordx4 v[184:185], v[144:147], off
	v_mov_b64_e32 v[150:151], v[14:15]
	s_and_b64 vcc, exec, s[4:5]
	v_cvt_pk_bf16_f32 v144, v156, v157
	v_cvt_pk_bf16_f32 v145, v158, v159
	v_cvt_pk_bf16_f32 v146, v152, v153
	v_cvt_pk_bf16_f32 v147, v154, v155
	global_store_dwordx4 v[184:185], v[144:147], off offset:64
	v_add_u32_e32 v184, 0xa0, v180
	v_mov_b64_e32 v[154:155], v[18:19]
	v_mov_b64_e32 v[158:159], v[30:31]
	v_mov_b64_e32 v[146:147], v[42:43]
	v_ashrrev_i32_e32 v185, 31, v184
	v_mov_b64_e32 v[152:153], v[16:17]
	v_mov_b64_e32 v[156:157], v[28:29]
	v_mov_b64_e32 v[148:149], v[12:13]
	v_mov_b64_e32 v[144:145], v[40:41]
	s_cbranch_vccnz .LBB0_285
	v_mov_b32_e32 v146, v41
	v_mov_b32_e32 v147, v13
	v_mov_b32_e32 v144, v40
	v_mov_b32_e32 v145, v12
	v_pk_mul_f32 v[146:147], v[146:147], v[146:147]
	v_mov_b32_e32 v148, v29
	v_pk_fma_f32 v[144:145], v[144:145], v[144:145], v[146:147]
	v_mov_b32_e32 v146, v42
	v_mov_b32_e32 v147, v14
	v_pk_fma_f32 v[144:145], v[146:147], v[146:147], v[144:145]
	v_mov_b32_e32 v146, v43
	v_mov_b32_e32 v147, v15
	v_mov_b32_e32 v149, v17
	v_pk_fma_f32 v[144:145], v[146:147], v[146:147], v[144:145]
	v_mov_b32_e32 v146, v28
	v_mov_b32_e32 v147, v16
	v_pk_mul_f32 v[148:149], v[148:149], v[148:149]
	v_add_f32_e32 v144, v144, v145
	v_pk_fma_f32 v[146:147], v[146:147], v[146:147], v[148:149]
	v_mov_b32_e32 v148, v30
	v_mov_b32_e32 v149, v18
	v_pk_fma_f32 v[146:147], v[148:149], v[148:149], v[146:147]
	v_mov_b32_e32 v148, v31
	v_mov_b32_e32 v149, v19
	v_pk_fma_f32 v[146:147], v[148:149], v[148:149], v[146:147]
	v_mov_b32_e32 v190, v176
	v_add_f32_e32 v144, v144, v146
	v_add_f32_e32 v144, v144, v147
	ds_bpermute_b32 v145, v196, v144
	v_pk_mul_f32 v[146:147], v[40:41], v[140:141]
	v_mov_b32_e32 v191, v176
	s_waitcnt lgkmcnt(0)
	v_add_f32_e32 v144, v144, v145
	ds_bpermute_b32 v145, v197, v144
	s_waitcnt lgkmcnt(0)
	v_add_f32_e32 v144, v144, v145
	v_fmamk_f32 v144, v144, 0x3c800000, v253
	v_rsq_f32_e32 v186, v144
	v_pk_mul_f32 v[144:145], v[42:43], v[142:143]
	v_pk_mul_f32 v[154:155], v[146:147], v[186:187] op_sel_hi:[1,0]
	v_pk_mul_f32 v[152:153], v[144:145], v[186:187] op_sel_hi:[1,0]
	v_lshlrev_b64 v[144:145], 8, v[184:185]
	v_lshl_add_u64 v[144:145], s[22:23], 0, v[144:145]
	v_lshl_add_u64 v[156:157], v[182:183], 3, v[144:145]
	s_waitcnt vmcnt(2)
	v_mov_b64_e32 v[148:149], v[224:225]
	v_mov_b64_e32 v[150:151], v[226:227]
	v_mov_b64_e32 v[144:145], v[228:229]
	v_mov_b64_e32 v[146:147], v[230:231]
	v_lshl_add_u64 v[248:249], v[156:157], 0, s[98:99]
	global_load_dwordx4 v[208:211], v[248:249], off offset:16
	global_load_dwordx4 v[212:215], v[248:249], off
	global_load_dwordx4 v[216:219], v[248:249], off offset:144
	global_load_dwordx4 v[220:223], v[248:249], off offset:128
	v_pk_mul_f32 v[158:159], v[144:145], v[154:155] op_sel:[1,1] op_sel_hi:[0,1]
	v_pk_fma_f32 v[200:201], v[144:145], v[154:155], v[158:159] op_sel_hi:[1,0,1] neg_lo:[0,0,1] neg_hi:[0,0,1]
	v_pk_fma_f32 v[144:145], v[144:145], v[154:155], v[158:159] op_sel_hi:[1,0,1]
	v_pk_mul_f32 v[154:155], v[146:147], v[152:153] op_sel:[1,1] op_sel_hi:[0,1]
	v_pk_fma_f32 v[158:159], v[146:147], v[152:153], v[154:155] op_sel_hi:[1,0,1] neg_lo:[0,0,1] neg_hi:[0,0,1]
	v_pk_fma_f32 v[146:147], v[146:147], v[152:153], v[154:155] op_sel_hi:[1,0,1]
	v_pk_mul_f32 v[154:155], v[12:13], v[136:137]
	v_mov_b32_e32 v159, v147
	v_pk_mul_f32 v[152:153], v[14:15], v[138:139]
	v_pk_mul_f32 v[154:155], v[154:155], v[186:187] op_sel_hi:[1,0]
	v_pk_mul_f32 v[146:147], v[190:191], v[158:159]
	v_mov_b32_e32 v201, v145
	v_pk_mul_f32 v[152:153], v[152:153], v[186:187] op_sel_hi:[1,0]
	v_pk_mul_f32 v[158:159], v[148:149], v[154:155] op_sel:[1,1] op_sel_hi:[0,1]
	v_pk_mul_f32 v[144:145], v[176:177], v[200:201]
	v_pk_fma_f32 v[200:201], v[148:149], v[154:155], v[158:159] op_sel_hi:[1,0,1] neg_lo:[0,0,1] neg_hi:[0,0,1]
	v_pk_fma_f32 v[148:149], v[148:149], v[154:155], v[158:159] op_sel_hi:[1,0,1]
	v_pk_mul_f32 v[154:155], v[150:151], v[152:153] op_sel:[1,1] op_sel_hi:[0,1]
	v_pk_fma_f32 v[158:159], v[150:151], v[152:153], v[154:155] op_sel_hi:[1,0,1] neg_lo:[0,0,1] neg_hi:[0,0,1]
	v_pk_fma_f32 v[150:151], v[150:151], v[152:153], v[154:155] op_sel_hi:[1,0,1]
	v_mov_b32_e32 v201, v149
	v_mov_b32_e32 v159, v151
	v_pk_mul_f32 v[152:153], v[30:31], v[134:135]
	v_pk_mul_f32 v[154:155], v[28:29], v[132:133]
	v_pk_mul_f32 v[150:151], v[190:191], v[158:159]
	v_pk_mul_f32 v[148:149], v[176:177], v[200:201]
	v_pk_mul_f32 v[200:201], v[152:153], v[186:187] op_sel_hi:[1,0]
	v_pk_mul_f32 v[202:203], v[154:155], v[186:187] op_sel_hi:[1,0]
	v_mov_b64_e32 v[152:153], v[234:235]
	v_mov_b64_e32 v[154:155], v[236:237]
	v_mov_b64_e32 v[156:157], v[238:239]
	v_mov_b64_e32 v[158:159], v[240:241]
	v_pk_mul_f32 v[204:205], v[156:157], v[202:203] op_sel:[1,1] op_sel_hi:[0,1]
	v_pk_fma_f32 v[206:207], v[156:157], v[202:203], v[204:205] op_sel_hi:[1,0,1] neg_lo:[0,0,1] neg_hi:[0,0,1]
	v_pk_fma_f32 v[156:157], v[156:157], v[202:203], v[204:205] op_sel_hi:[1,0,1]
	v_pk_mul_f32 v[202:203], v[158:159], v[200:201] op_sel:[1,1] op_sel_hi:[0,1]
	v_pk_fma_f32 v[204:205], v[158:159], v[200:201], v[202:203] op_sel_hi:[1,0,1] neg_lo:[0,0,1] neg_hi:[0,0,1]
	v_pk_fma_f32 v[158:159], v[158:159], v[200:201], v[202:203] op_sel_hi:[1,0,1]
	v_pk_mul_f32 v[200:201], v[18:19], v[130:131]
	v_pk_mul_f32 v[202:203], v[16:17], v[128:129]
	v_pk_mul_f32 v[200:201], v[200:201], v[186:187] op_sel_hi:[1,0]
	v_pk_mul_f32 v[186:187], v[202:203], v[186:187] op_sel_hi:[1,0]
	v_mov_b32_e32 v205, v159
	v_pk_mul_f32 v[202:203], v[152:153], v[186:187] op_sel:[1,1] op_sel_hi:[0,1]
	v_pk_mul_f32 v[158:159], v[190:191], v[204:205]
	v_pk_fma_f32 v[204:205], v[152:153], v[186:187], v[202:203] op_sel_hi:[1,0,1] neg_lo:[0,0,1] neg_hi:[0,0,1]
	v_pk_fma_f32 v[152:153], v[152:153], v[186:187], v[202:203] op_sel_hi:[1,0,1]
	v_pk_mul_f32 v[186:187], v[154:155], v[200:201] op_sel:[1,1] op_sel_hi:[0,1]
	v_pk_fma_f32 v[202:203], v[154:155], v[200:201], v[186:187] op_sel_hi:[1,0,1] neg_lo:[0,0,1] neg_hi:[0,0,1]
	v_pk_fma_f32 v[154:155], v[154:155], v[200:201], v[186:187] op_sel_hi:[1,0,1]
	v_mov_b32_e32 v207, v157
	v_mov_b32_e32 v203, v155
	v_mov_b32_e32 v205, v153
	v_pk_mul_f32 v[156:157], v[176:177], v[206:207]
	v_pk_mul_f32 v[154:155], v[190:191], v[202:203]
	v_pk_mul_f32 v[152:153], v[176:177], v[204:205]
; __device__ __forceinline__ unsigned cvt_pk_bf16(float lo, float hi) { f32x2_c v = {lo, hi}; bf16x2_c b = __builtin_convertvector(v, bf16x2_c); return __builtin_bit_cast(unsigned, b); }
;     __device__ __forceinline__ void operator()(const f32x4 (&acc)[2][2][4][2], const Unit& u, int wr, int wc, int fr, int fq) const {
;     ...
;                 for (int m = 0; m < 4; ++m) { const int row = row0 + ai * HALF + m * 16; bf16_t* rowp = PROJ + (size_t)row * PP + pn * 256 + 64 * wc + 8 * fq;
;                     f32x4 v[2][2];
; #pragma unroll
;                     for (int bj = 0; bj < 2; ++bj)
; #pragma unroll
;                         for (int n = 0; n < 2; ++n) v[bj][n] = acc[ai][bj][m][n];
;                     if (nrm) {
;                         float ss = 0.f;
; #pragma unroll
;                         for (int bj = 0; bj < 2; ++bj)
; #pragma unroll
;                             for (int n = 0; n < 2; ++n) ss += v[bj][n][0] * v[bj][n][0] + v[bj][n][1] * v[bj][n][1] + v[bj][n][2] * v[bj][n][2] + v[bj][n][3] * v[bj][n][3];
;                         ss += __shfl_xor(ss, 16); ss += __shfl_xor(ss, 32);
;                         const float rinv = __builtin_amdgcn_rsqf(ss * (1.f / 64.f) + EPS);
; #pragma unroll
;                         for (int bj = 0; bj < 2; ++bj)
; #pragma unroll
;                             for (int n = 0; n < 2; ++n) { const f32x4 x = v[bj][n] * wv[bj][n] * rinv; const f32x4 cs = *(const f32x4*)(CS + ((size_t)row * 32 + 16 * bj + 4 * fq + 2 * n) * 2);
;                                 f32x4 o; o[0] = x[0] * cs[0] - x[1] * cs[1]; o[1] = x[0] * cs[1] + x[1] * cs[0]; o[2] = x[2] * cs[2] - x[3] * cs[3]; o[3] = x[2] * cs[3] + x[3] * cs[2]; v[bj][n] = o * sc; }
;                     }
; #pragma unroll
;                     for (int bj = 0; bj < 2; ++bj) { u32x4 w; w.x = cvt_pk_bf16(v[bj][0][0], v[bj][0][1]); w.y = cvt_pk_bf16(v[bj][0][2], v[bj][0][3]); w.z = cvt_pk_bf16(v[bj][1][0], v[bj][1][1]); w.w = cvt_pk_bf16(v[bj][1][2], v[bj][1][3]);
;                         *(u32x4*)(rowp + 32 * bj) = w; } }
.LBB0_285:
	v_mov_b64_e32 v[186:187], s[24:25]
	v_mad_i64_i32 v[184:185], s[62:63], v184, s64, v[186:187]
	v_lshl_add_u64 v[184:185], v[184:185], 0, s[56:57]
	v_lshl_add_u64 v[184:185], v[184:185], 0, s[78:79]
	v_lshl_add_u64 v[184:185], v[178:179], 1, v[184:185]
	v_cvt_pk_bf16_f32 v144, v144, v145
	v_cvt_pk_bf16_f32 v145, v146, v147
	v_cvt_pk_bf16_f32 v146, v148, v149
	v_cvt_pk_bf16_f32 v147, v150, v151
	global_store_dwordx4 v[184:185], v[144:147], off
	v_add_u32_e32 v180, 0xb0, v180
	v_mov_b64_e32 v[150:151], v[2:3]
	v_cvt_pk_bf16_f32 v144, v156, v157
	v_cvt_pk_bf16_f32 v145, v158, v159
	v_cvt_pk_bf16_f32 v146, v152, v153
	v_cvt_pk_bf16_f32 v147, v154, v155
	global_store_dwordx4 v[184:185], v[144:147], off offset:64
	v_mov_b64_e32 v[158:159], v[6:7]
	v_mov_b64_e32 v[154:155], v[10:11]
	v_mov_b64_e32 v[146:147], v[22:23]
	v_ashrrev_i32_e32 v181, 31, v180
	s_and_b64 vcc, exec, s[4:5]
	v_mov_b64_e32 v[156:157], v[4:5]
	v_mov_b64_e32 v[152:153], v[8:9]
	v_mov_b64_e32 v[148:149], v[0:1]
	v_mov_b64_e32 v[144:145], v[20:21]
	s_cbranch_vccnz .LBB0_287
	v_mov_b32_e32 v146, v21
	v_mov_b32_e32 v147, v1
	v_mov_b32_e32 v144, v20
	v_mov_b32_e32 v145, v0
	v_pk_mul_f32 v[146:147], v[146:147], v[146:147]
	v_mov_b32_e32 v148, v9
	v_pk_fma_f32 v[144:145], v[144:145], v[144:145], v[146:147]
	v_mov_b32_e32 v146, v22
	v_mov_b32_e32 v147, v2
	v_pk_fma_f32 v[144:145], v[146:147], v[146:147], v[144:145]
	v_mov_b32_e32 v146, v23
	v_mov_b32_e32 v147, v3
	v_mov_b32_e32 v149, v5
	v_pk_fma_f32 v[144:145], v[146:147], v[146:147], v[144:145]
	v_mov_b32_e32 v146, v8
	v_mov_b32_e32 v147, v4
	v_pk_mul_f32 v[148:149], v[148:149], v[148:149]
	v_add_f32_e32 v144, v144, v145
	v_pk_fma_f32 v[146:147], v[146:147], v[146:147], v[148:149]
	v_mov_b32_e32 v148, v10
	v_mov_b32_e32 v149, v6
	v_pk_fma_f32 v[146:147], v[148:149], v[148:149], v[146:147]
	v_mov_b32_e32 v148, v11
	v_mov_b32_e32 v149, v7
	v_pk_fma_f32 v[146:147], v[148:149], v[148:149], v[146:147]
	s_waitcnt vmcnt(2)
	v_pk_mul_f32 v[140:141], v[20:21], v[140:141]
	v_add_f32_e32 v144, v144, v146
	v_add_f32_e32 v144, v144, v147
	ds_bpermute_b32 v145, v196, v144
	v_pk_mul_f32 v[142:143], v[22:23], v[142:143]
	v_pk_mul_f32 v[136:137], v[0:1], v[136:137]
	v_pk_mul_f32 v[138:139], v[2:3], v[138:139]
	v_pk_mul_f32 v[134:135], v[10:11], v[134:135]
	s_waitcnt lgkmcnt(0)
	v_add_f32_e32 v144, v144, v145
	ds_bpermute_b32 v145, v197, v144
	v_pk_mul_f32 v[132:133], v[8:9], v[132:133]
	v_pk_mul_f32 v[128:129], v[4:5], v[128:129]
	v_pk_mul_f32 v[130:131], v[6:7], v[130:131]
	s_waitcnt lgkmcnt(0)
	v_add_f32_e32 v144, v144, v145
	v_fmamk_f32 v144, v144, 0x3c800000, v253
	v_rsq_f32_e32 v156, v144
	s_nop 0
	v_pk_mul_f32 v[146:147], v[140:141], v[156:157] op_sel_hi:[1,0]
	v_lshlrev_b64 v[140:141], 8, v[180:181]
	v_lshl_add_u64 v[140:141], s[22:23], 0, v[140:141]
	v_lshl_add_u64 v[152:153], v[182:183], 3, v[140:141]
	v_pk_mul_f32 v[144:145], v[142:143], v[156:157] op_sel_hi:[1,0]
	v_mov_b64_e32 v[148:149], v[208:209]
	v_mov_b64_e32 v[150:151], v[210:211]
	v_mov_b64_e32 v[140:141], v[212:213]
	v_mov_b64_e32 v[142:143], v[214:215]
	v_pk_mul_f32 v[136:137], v[136:137], v[156:157] op_sel_hi:[1,0]
	v_pk_mul_f32 v[138:139], v[138:139], v[156:157] op_sel_hi:[1,0]
	v_pk_mul_f32 v[128:129], v[128:129], v[156:157] op_sel_hi:[1,0]
	v_pk_mul_f32 v[130:131], v[130:131], v[156:157] op_sel_hi:[1,0]
	v_pk_mul_f32 v[154:155], v[140:141], v[146:147] op_sel:[1,1] op_sel_hi:[0,1]
	v_pk_fma_f32 v[158:159], v[140:141], v[146:147], v[154:155] op_sel_hi:[1,0,1] neg_lo:[0,0,1] neg_hi:[0,0,1]
	v_pk_fma_f32 v[154:155], v[140:141], v[146:147], v[154:155] op_sel_hi:[1,0,1]
	v_pk_mul_f32 v[140:141], v[142:143], v[144:145] op_sel:[1,1] op_sel_hi:[0,1]
	v_pk_fma_f32 v[146:147], v[142:143], v[144:145], v[140:141] op_sel_hi:[1,0,1] neg_lo:[0,0,1] neg_hi:[0,0,1]
	v_pk_fma_f32 v[140:141], v[142:143], v[144:145], v[140:141] op_sel_hi:[1,0,1]
	v_pk_mul_f32 v[142:143], v[148:149], v[136:137] op_sel:[1,1] op_sel_hi:[0,1]
	v_mov_b32_e32 v159, v155
	v_pk_fma_f32 v[154:155], v[148:149], v[136:137], v[142:143] op_sel_hi:[1,0,1] neg_lo:[0,0,1] neg_hi:[0,0,1]
	v_pk_fma_f32 v[136:137], v[148:149], v[136:137], v[142:143] op_sel_hi:[1,0,1]
	v_pk_mul_f32 v[142:143], v[150:151], v[138:139] op_sel:[1,1] op_sel_hi:[0,1]
	v_pk_fma_f32 v[148:149], v[150:151], v[138:139], v[142:143] op_sel_hi:[1,0,1] neg_lo:[0,0,1] neg_hi:[0,0,1]
	v_pk_fma_f32 v[138:139], v[150:151], v[138:139], v[142:143] op_sel_hi:[1,0,1]
	v_mov_b32_e32 v147, v141
	v_mov_b32_e32 v140, v176
	v_mov_b32_e32 v141, v176
	v_mov_b32_e32 v149, v139
	v_mov_b32_e32 v155, v137
	v_pk_mul_f32 v[150:151], v[140:141], v[148:149]
	v_pk_mul_f32 v[148:149], v[176:177], v[154:155]
	v_pk_mul_f32 v[142:143], v[134:135], v[156:157] op_sel_hi:[1,0]
	v_pk_mul_f32 v[154:155], v[132:133], v[156:157] op_sel_hi:[1,0]
	v_mov_b64_e32 v[132:133], v[216:217]
	v_mov_b64_e32 v[134:135], v[218:219]
	v_mov_b64_e32 v[136:137], v[220:221]
	v_mov_b64_e32 v[138:139], v[222:223]
	v_pk_mul_f32 v[144:145], v[176:177], v[158:159]
	v_pk_mul_f32 v[146:147], v[140:141], v[146:147]
	v_pk_mul_f32 v[152:153], v[136:137], v[154:155] op_sel:[1,1] op_sel_hi:[0,1]
	v_pk_fma_f32 v[158:159], v[136:137], v[154:155], v[152:153] op_sel_hi:[1,0,1] neg_lo:[0,0,1] neg_hi:[0,0,1]
	v_pk_fma_f32 v[136:137], v[136:137], v[154:155], v[152:153] op_sel_hi:[1,0,1]
	v_pk_mul_f32 v[152:153], v[138:139], v[142:143] op_sel:[1,1] op_sel_hi:[0,1]
	v_pk_fma_f32 v[154:155], v[138:139], v[142:143], v[152:153] op_sel_hi:[1,0,1] neg_lo:[0,0,1] neg_hi:[0,0,1]
	v_pk_fma_f32 v[138:139], v[138:139], v[142:143], v[152:153] op_sel_hi:[1,0,1]
	v_mov_b32_e32 v159, v137
	v_pk_mul_f32 v[136:137], v[132:133], v[128:129] op_sel:[1,1] op_sel_hi:[0,1]
	v_mov_b32_e32 v155, v139
	v_pk_fma_f32 v[138:139], v[132:133], v[128:129], v[136:137] op_sel_hi:[1,0,1] neg_lo:[0,0,1] neg_hi:[0,0,1]
	v_pk_fma_f32 v[128:129], v[132:133], v[128:129], v[136:137] op_sel_hi:[1,0,1]
	v_pk_mul_f32 v[132:133], v[134:135], v[130:131] op_sel:[1,1] op_sel_hi:[0,1]
	v_pk_fma_f32 v[136:137], v[134:135], v[130:131], v[132:133] op_sel_hi:[1,0,1] neg_lo:[0,0,1] neg_hi:[0,0,1]
	v_pk_fma_f32 v[130:131], v[134:135], v[130:131], v[132:133] op_sel_hi:[1,0,1]
	v_mov_b32_e32 v139, v129
	v_mov_b32_e32 v137, v131
	v_pk_mul_f32 v[154:155], v[140:141], v[154:155]
	v_pk_mul_f32 v[152:153], v[176:177], v[158:159]
	v_pk_mul_f32 v[158:159], v[140:141], v[136:137]
	v_pk_mul_f32 v[156:157], v[176:177], v[138:139]
